# v64 + back-edge rotation (guide 7.11) on the five GEMM K-loops: counter/pointer update/exit test moved in front of the loop-back barrier, barrier is the loop head
# baseline (speedup 1.0000x reference)
; #define PG8_STAGE(bufoff, gbase, voff) do { _Pragma("unroll") for (int _i = 0; _i < 2; ++_i) \
;         __builtin_amdgcn_global_load_lds((const unsigned*)((const char*)(gbase) + (voff)[_i]), (PG8_LAS unsigned*)(lds + (bufoff) + ldsw + _i * 8192), 16, 0, 0); } while (0)
; #define PG8_LDA(dst, b, h) do { _Pragma("unroll") for (int m = 0; m < 4; ++m) _Pragma("unroll") for (int k = 0; k < 2; ++k) dst[m][k] = *(const PG8_LAS bf16x8*)(lds + PG8_SA(b, h) + aoff + m * 2048 + k * 1024); } while (0)
; #define PG8_LDB(dst, b, h) do { _Pragma("unroll") for (int n = 0; n < 2; ++n) _Pragma("unroll") for (int k = 0; k < 2; ++k) dst[n][k] = *(const PG8_LAS bf16x8*)(lds + PG8_SB(b, h) + boff + n * 2048 + k * 1024); } while (0)
; #define PG8_MMA(ai, bj, At, Bt) do { __builtin_amdgcn_s_setprio(1); _Pragma("unroll") for (int m = 0; m < 4; ++m) _Pragma("unroll") for (int n = 0; n < 2; ++n) _Pragma("unroll") for (int k = 0; k < 2; ++k) \
;         acc[ai][bj][m][n] = __builtin_amdgcn_mfma_f32_16x16x32_bf16(Bt[n][k], At[m][k], acc[ai][bj][m][n], 0, 0, 0); __builtin_amdgcn_s_setprio(0); } while (0)
; #define PG8_WAIT_V(n) asm volatile("s_waitcnt vmcnt(" #n ")" ::: "memory")
; template <class Epi, class Sched, bool ALIGN_EPI = false, bool SP2 = false>
; __device__ __forceinline__ void gemm_phase(PG8_LAS unsigned char* lds, const Gemm g, const Sched& S, const Epi& E, int wid) {
;     ...
;         for (int t = 0; t < nt; t += 2) {
;             const bool last = (t == nt - 2);
;             const char* a1 = cA + (size_t)(t + 1) * kstep;
;             const char* a2 = last ? nA : cA + (size_t)(t + 2) * kstep; const char* b2 = last ? nB : cB + (size_t)(t + 2) * kstep;
;             const char* a3 = a2 + kstep; const char* b3 = b2 + kstep;
;             if (last && has_next) S.a_ready(nxt);
;             if constexpr (SP2) {
;             PG8_LDB(B0, 0, 0); PG8_LDB(B1, 0, 1); PG8_SCHED; PG8_LDA(At, 0, 0); PG8_STAGE(PG8_SA(1, 1), a1 + hstepA, voffA);
;             PG8_WAIT_V(8); PG8_WAIT_L(0); PG8_BAR; PG8_MMA(0, 0, At, B0); PG8_MMA(0, 1, At, B1); PG8_BAR; PG8_SCHED;
;     ...
; #pragma unroll
;         for (int a = 0; a < 2; ++a)
; #pragma unroll
;             for (int b = 0; b < 2; ++b)
; #pragma unroll
;                 for (int m = 0; m < 4; ++m)
; #pragma unroll
;                     for (int n = 0; n < 2; ++n) acc[a][b][m][n] = (f32x4){0.f, 0.f, 0.f, 0.f};
.LBB0_232:
	s_add_u32 s64, s50, 0x100
	v_mov_b32_e32 v0, 0
	s_addc_u32 s65, s51, 0
	s_mov_b32 s66, -2
	v_mov_b32_e32 v1, v0
	v_mov_b32_e32 v2, v0
	v_mov_b32_e32 v3, v0
	v_mov_b32_e32 v8, v0
	v_mov_b32_e32 v9, v0
	v_mov_b32_e32 v10, v0
	v_mov_b32_e32 v11, v0
	v_mov_b32_e32 v16, v0
	v_mov_b32_e32 v17, v0
	v_mov_b32_e32 v18, v0
	v_mov_b32_e32 v19, v0
	v_mov_b32_e32 v24, v0
	v_mov_b32_e32 v25, v0
	v_mov_b32_e32 v26, v0
	v_mov_b32_e32 v27, v0
	v_mov_b32_e32 v32, v0
	v_mov_b32_e32 v33, v0
	v_mov_b32_e32 v34, v0
	v_mov_b32_e32 v35, v0
	v_mov_b32_e32 v40, v0
	v_mov_b32_e32 v41, v0
	v_mov_b32_e32 v42, v0
	v_mov_b32_e32 v43, v0
	v_mov_b32_e32 v48, v0
	v_mov_b32_e32 v49, v0
	v_mov_b32_e32 v50, v0
	v_mov_b32_e32 v51, v0
	v_mov_b32_e32 v56, v0
	v_mov_b32_e32 v57, v0
	v_mov_b32_e32 v58, v0
	v_mov_b32_e32 v59, v0
	v_mov_b32_e32 v4, v0
	v_mov_b32_e32 v5, v0
	v_mov_b32_e32 v6, v0
	v_mov_b32_e32 v7, v0
	v_mov_b32_e32 v12, v0
	v_mov_b32_e32 v13, v0
	v_mov_b32_e32 v14, v0
	v_mov_b32_e32 v15, v0
	v_mov_b32_e32 v20, v0
	v_mov_b32_e32 v21, v0
	v_mov_b32_e32 v22, v0
	v_mov_b32_e32 v23, v0
	v_mov_b32_e32 v28, v0
	v_mov_b32_e32 v29, v0
	v_mov_b32_e32 v30, v0
	v_mov_b32_e32 v31, v0
	v_mov_b32_e32 v36, v0
	v_mov_b32_e32 v37, v0
	v_mov_b32_e32 v38, v0
	v_mov_b32_e32 v39, v0
	v_mov_b32_e32 v44, v0
	v_mov_b32_e32 v45, v0
	v_mov_b32_e32 v46, v0
	v_mov_b32_e32 v47, v0
	v_mov_b32_e32 v52, v0
	v_mov_b32_e32 v53, v0
	v_mov_b32_e32 v54, v0
	v_mov_b32_e32 v55, v0
	v_mov_b32_e32 v60, v0
	v_mov_b32_e32 v61, v0
	v_mov_b32_e32 v62, v0
	v_mov_b32_e32 v63, v0
	v_mov_b32_e32 v64, v0
	v_mov_b32_e32 v65, v0
	v_mov_b32_e32 v66, v0
	v_mov_b32_e32 v67, v0
	v_mov_b32_e32 v72, v0
	v_mov_b32_e32 v73, v0
	v_mov_b32_e32 v74, v0
	v_mov_b32_e32 v75, v0
	v_mov_b32_e32 v80, v0
	v_mov_b32_e32 v81, v0
	v_mov_b32_e32 v82, v0
	v_mov_b32_e32 v83, v0
	v_mov_b32_e32 v88, v0
	v_mov_b32_e32 v89, v0
	v_mov_b32_e32 v90, v0
	v_mov_b32_e32 v91, v0
	v_mov_b32_e32 v96, v0
	v_mov_b32_e32 v97, v0
	v_mov_b32_e32 v98, v0
	v_mov_b32_e32 v99, v0
	v_mov_b32_e32 v116, v0
	v_mov_b32_e32 v117, v0
	v_mov_b32_e32 v118, v0
	v_mov_b32_e32 v119, v0
	v_mov_b32_e32 v120, v0
	v_mov_b32_e32 v121, v0
	v_mov_b32_e32 v122, v0
	v_mov_b32_e32 v123, v0
	v_mov_b32_e32 v124, v0
	v_mov_b32_e32 v125, v0
	v_mov_b32_e32 v126, v0
	v_mov_b32_e32 v127, v0
	v_mov_b32_e32 v68, v0
	v_mov_b32_e32 v69, v0
	v_mov_b32_e32 v70, v0
	v_mov_b32_e32 v71, v0
	v_mov_b32_e32 v76, v0
	v_mov_b32_e32 v77, v0
	v_mov_b32_e32 v78, v0
	v_mov_b32_e32 v79, v0
	v_mov_b32_e32 v84, v0
	v_mov_b32_e32 v85, v0
	v_mov_b32_e32 v86, v0
	v_mov_b32_e32 v87, v0
	v_mov_b32_e32 v92, v0
	v_mov_b32_e32 v93, v0
	v_mov_b32_e32 v94, v0
	v_mov_b32_e32 v95, v0
	v_mov_b32_e32 v100, v0
	v_mov_b32_e32 v101, v0
	v_mov_b32_e32 v102, v0
	v_mov_b32_e32 v103, v0
	v_mov_b32_e32 v104, v0
	v_mov_b32_e32 v105, v0
	v_mov_b32_e32 v106, v0
	v_mov_b32_e32 v107, v0
	v_mov_b32_e32 v108, v0
	v_mov_b32_e32 v109, v0
	v_mov_b32_e32 v110, v0
	v_mov_b32_e32 v111, v0
	v_mov_b32_e32 v112, v0
	v_mov_b32_e32 v113, v0
	v_mov_b32_e32 v114, v0
	v_mov_b32_e32 v115, v0
	s_branch .LBB0_233
.Lrot_head_0:
	s_barrier
.LBB0_233:
	ds_read_b128 v[144:147], v155
	ds_read_b128 v[148:151], v155 offset:1024
	ds_read_b128 v[160:163], v155 offset:2048
	ds_read_b128 v[164:167], v155 offset:3072
	ds_read_b128 v[168:171], v156
	ds_read_b128 v[172:175], v156 offset:1024
	ds_read_b128 v[176:179], v156 offset:2048
	ds_read_b128 v[180:183], v156 offset:3072
	s_add_u32 s4, s48, 0x100
	s_addc_u32 s5, s49, 0
	s_add_u32 s98, s48, 0x80
	s_addc_u32 s99, s49, 0
	s_add_u32 s100, s48, 0x104080
	s_addc_u32 s101, s49, 0
	s_cmp_eq_u32 s66, 60
	s_cselect_b32 s53, s45, s5
	s_cselect_b32 s52, s44, s4
	s_cselect_b32 s51, s47, s65
	s_cselect_b32 s50, s46, s64
	s_add_i32 m0, s23, 0xc000
	ds_read_b128 v[184:187], v157
	ds_read_b128 v[188:191], v157 offset:1024
	ds_read_b128 v[192:195], v157 offset:2048
	ds_read_b128 v[196:199], v157 offset:3072
	ds_read_b128 v[200:203], v157 offset:4096
	ds_read_b128 v[204:207], v157 offset:5120
	ds_read_b128 v[208:211], v157 offset:6144
	ds_read_b128 v[212:215], v157 offset:7168
	global_load_lds_dwordx4 v134, s[100:101]
	s_add_i32 m0, s23, 0xe000
	s_nop 0
	global_load_lds_dwordx4 v130, s[100:101]
	s_mov_b32 m0, s55
	s_nop 0
	global_load_lds_dwordx4 v134, s[98:99]
	s_mov_b32 m0, s56
	s_nop 0
	global_load_lds_dwordx4 v130, s[98:99]
	s_waitcnt vmcnt(8)
	s_waitcnt lgkmcnt(0)
	s_barrier
	s_waitcnt lgkmcnt(0)
	v_mfma_f32_16x16x32_bf16 v[112:115], v[144:147], v[184:187], v[112:115]
	v_mfma_f32_16x16x32_bf16 v[108:111], v[160:163], v[184:187], v[108:111]
	v_mfma_f32_16x16x32_bf16 v[104:107], v[144:147], v[192:195], v[104:107]
	v_mfma_f32_16x16x32_bf16 v[100:103], v[160:163], v[192:195], v[100:103]
	v_mfma_f32_16x16x32_bf16 v[92:95], v[144:147], v[200:203], v[92:95]
	v_mfma_f32_16x16x32_bf16 v[84:87], v[160:163], v[200:203], v[84:87]
	v_mfma_f32_16x16x32_bf16 v[76:79], v[144:147], v[208:211], v[76:79]
	v_mfma_f32_16x16x32_bf16 v[68:71], v[160:163], v[208:211], v[68:71]
	v_mfma_f32_16x16x32_bf16 v[112:115], v[148:151], v[188:191], v[112:115]
	v_mfma_f32_16x16x32_bf16 v[108:111], v[164:167], v[188:191], v[108:111]
	v_mfma_f32_16x16x32_bf16 v[104:107], v[148:151], v[196:199], v[104:107]
	v_mfma_f32_16x16x32_bf16 v[100:103], v[164:167], v[196:199], v[100:103]
	v_mfma_f32_16x16x32_bf16 v[92:95], v[148:151], v[204:207], v[92:95]
	v_mfma_f32_16x16x32_bf16 v[84:87], v[164:167], v[204:207], v[84:87]
	v_mfma_f32_16x16x32_bf16 v[76:79], v[148:151], v[212:215], v[76:79]
	v_mfma_f32_16x16x32_bf16 v[68:71], v[164:167], v[212:215], v[68:71]
	v_mfma_f32_16x16x32_bf16 v[124:127], v[168:171], v[184:187], v[124:127]
	v_mfma_f32_16x16x32_bf16 v[120:123], v[176:179], v[184:187], v[120:123]
	v_mfma_f32_16x16x32_bf16 v[116:119], v[168:171], v[192:195], v[116:119]
	v_mfma_f32_16x16x32_bf16 v[96:99], v[176:179], v[192:195], v[96:99]
	v_mfma_f32_16x16x32_bf16 v[88:91], v[168:171], v[200:203], v[88:91]
	v_mfma_f32_16x16x32_bf16 v[80:83], v[176:179], v[200:203], v[80:83]
	v_mfma_f32_16x16x32_bf16 v[72:75], v[168:171], v[208:211], v[72:75]
	v_mfma_f32_16x16x32_bf16 v[64:67], v[176:179], v[208:211], v[64:67]
	v_mfma_f32_16x16x32_bf16 v[124:127], v[172:175], v[188:191], v[124:127]
	v_mfma_f32_16x16x32_bf16 v[120:123], v[180:183], v[188:191], v[120:123]
	v_mfma_f32_16x16x32_bf16 v[116:119], v[172:175], v[196:199], v[116:119]
	v_mfma_f32_16x16x32_bf16 v[96:99], v[180:183], v[196:199], v[96:99]
	v_mfma_f32_16x16x32_bf16 v[88:91], v[172:175], v[204:207], v[88:91]
	v_mfma_f32_16x16x32_bf16 v[80:83], v[180:183], v[204:207], v[80:83]
	v_mfma_f32_16x16x32_bf16 v[72:75], v[172:175], v[212:215], v[72:75]
	v_mfma_f32_16x16x32_bf16 v[64:67], v[180:183], v[212:215], v[64:67]
	s_barrier
; #define PG8_STAGE(bufoff, gbase, voff) do { _Pragma("unroll") for (int _i = 0; _i < 2; ++_i) \
;         __builtin_amdgcn_global_load_lds((const unsigned*)((const char*)(gbase) + (voff)[_i]), (PG8_LAS unsigned*)(lds + (bufoff) + ldsw + _i * 8192), 16, 0, 0); } while (0)
; #define PG8_STAGE_NT(bufoff, gbase, voff) do { _Pragma("unroll") for (int _i = 0; _i < 2; ++_i) \
;         __builtin_amdgcn_global_load_lds((const unsigned*)((const char*)(gbase) + (voff)[_i]), (PG8_LAS unsigned*)(lds + (bufoff) + ldsw + _i * 8192), 16, 0, PG8_B_AUX); } while (0)
; #define PG8_LDA(dst, b, h) do { _Pragma("unroll") for (int m = 0; m < 4; ++m) _Pragma("unroll") for (int k = 0; k < 2; ++k) dst[m][k] = *(const PG8_LAS bf16x8*)(lds + PG8_SA(b, h) + aoff + m * 2048 + k * 1024); } while (0)
; #define PG8_LDB(dst, b, h) do { _Pragma("unroll") for (int n = 0; n < 2; ++n) _Pragma("unroll") for (int k = 0; k < 2; ++k) dst[n][k] = *(const PG8_LAS bf16x8*)(lds + PG8_SB(b, h) + boff + n * 2048 + k * 1024); } while (0)
; #define PG8_MMA(ai, bj, At, Bt) do { __builtin_amdgcn_s_setprio(1); _Pragma("unroll") for (int m = 0; m < 4; ++m) _Pragma("unroll") for (int n = 0; n < 2; ++n) _Pragma("unroll") for (int k = 0; k < 2; ++k) \
;         acc[ai][bj][m][n] = __builtin_amdgcn_mfma_f32_16x16x32_bf16(Bt[n][k], At[m][k], acc[ai][bj][m][n], 0, 0, 0); __builtin_amdgcn_s_setprio(0); } while (0)
; #define PG8_WAIT_V(n) asm volatile("s_waitcnt vmcnt(" #n ")" ::: "memory")
; #define PG8_BAR __builtin_amdgcn_s_barrier()
; template <class Epi, class Sched, bool ALIGN_EPI = false, bool SP2 = false>
; __device__ __forceinline__ void gemm_phase(PG8_LAS unsigned char* lds, const Gemm g, const Sched& S, const Epi& E, int wid) {
;     ...
;             PG8_LDA(At, 0, 1); PG8_STAGE_NT(PG8_SB(0, 0), b2, voffB); PG8_STAGE_NT(PG8_SB(0, 1), b2 + hstepB, voffB); PG8_STAGE(PG8_SA(0, 0), a2, voffA);
;             PG8_WAIT_V(8); PG8_WAIT_L(0); PG8_BAR; PG8_MMA(1, 0, At, B0); PG8_MMA(1, 1, At, B1); PG8_BAR; PG8_SCHED;
;             PG8_LDB(B0, 1, 0); PG8_LDB(B1, 1, 1); PG8_SCHED; PG8_LDA(At, 1, 0); PG8_STAGE(PG8_SA(0, 1), a2 + hstepA, voffA);
;             PG8_WAIT_V(8); PG8_WAIT_L(0); PG8_BAR; PG8_MMA(0, 0, At, B0); PG8_MMA(0, 1, At, B1); PG8_BAR; PG8_SCHED;
;             PG8_LDA(At, 1, 1); PG8_STAGE_NT(PG8_SB(1, 0), b3, voffB); PG8_STAGE_NT(PG8_SB(1, 1), b3 + hstepB, voffB); PG8_STAGE(PG8_SA(1, 0), a3, voffA);
	s_add_i32 s48, s58, s17
	s_mov_b32 m0, s48
	ds_read_b128 v[184:187], v157 offset:16384
	ds_read_b128 v[188:191], v157 offset:17408
	ds_read_b128 v[192:195], v157 offset:18432
	ds_read_b128 v[196:199], v157 offset:19456
	ds_read_b128 v[200:203], v157 offset:20480
	ds_read_b128 v[204:207], v157 offset:21504
	ds_read_b128 v[208:211], v157 offset:22528
	ds_read_b128 v[212:215], v157 offset:23552
	global_load_lds_dwordx4 v132, s[50:51]
	s_add_i32 m0, s48, 0x2000
	s_add_u32 s48, s50, 0x104000
	s_addc_u32 s49, s51, 0
	s_add_i32 s67, s59, s17
	global_load_lds_dwordx4 v128, s[50:51]
	s_mov_b32 m0, s67
	s_nop 0
	global_load_lds_dwordx4 v132, s[48:49]
	s_add_i32 m0, s67, 0x2000
	s_nop 0
	global_load_lds_dwordx4 v128, s[48:49]
	s_waitcnt vmcnt(4)
	s_waitcnt lgkmcnt(0)
	s_barrier
	s_waitcnt lgkmcnt(0)
	v_mfma_f32_16x16x32_bf16 v[60:63], v[144:147], v[184:187], v[60:63]
	v_mfma_f32_16x16x32_bf16 v[52:55], v[160:163], v[184:187], v[52:55]
	v_mfma_f32_16x16x32_bf16 v[44:47], v[144:147], v[192:195], v[44:47]
	v_mfma_f32_16x16x32_bf16 v[36:39], v[160:163], v[192:195], v[36:39]
	v_mfma_f32_16x16x32_bf16 v[28:31], v[144:147], v[200:203], v[28:31]
	v_mfma_f32_16x16x32_bf16 v[20:23], v[160:163], v[200:203], v[20:23]
	v_mfma_f32_16x16x32_bf16 v[12:15], v[144:147], v[208:211], v[12:15]
	v_mfma_f32_16x16x32_bf16 v[4:7], v[160:163], v[208:211], v[4:7]
	v_mfma_f32_16x16x32_bf16 v[60:63], v[148:151], v[188:191], v[60:63]
	v_mfma_f32_16x16x32_bf16 v[52:55], v[164:167], v[188:191], v[52:55]
	v_mfma_f32_16x16x32_bf16 v[44:47], v[148:151], v[196:199], v[44:47]
	v_mfma_f32_16x16x32_bf16 v[36:39], v[164:167], v[196:199], v[36:39]
	v_mfma_f32_16x16x32_bf16 v[28:31], v[148:151], v[204:207], v[28:31]
	v_mfma_f32_16x16x32_bf16 v[20:23], v[164:167], v[204:207], v[20:23]
	v_mfma_f32_16x16x32_bf16 v[12:15], v[148:151], v[212:215], v[12:15]
	v_mfma_f32_16x16x32_bf16 v[4:7], v[164:167], v[212:215], v[4:7]
	v_mfma_f32_16x16x32_bf16 v[56:59], v[168:171], v[184:187], v[56:59]
	v_mfma_f32_16x16x32_bf16 v[48:51], v[176:179], v[184:187], v[48:51]
	v_mfma_f32_16x16x32_bf16 v[40:43], v[168:171], v[192:195], v[40:43]
	v_mfma_f32_16x16x32_bf16 v[32:35], v[176:179], v[192:195], v[32:35]
	v_mfma_f32_16x16x32_bf16 v[24:27], v[168:171], v[200:203], v[24:27]
	v_mfma_f32_16x16x32_bf16 v[16:19], v[176:179], v[200:203], v[16:19]
	v_mfma_f32_16x16x32_bf16 v[8:11], v[168:171], v[208:211], v[8:11]
	v_mfma_f32_16x16x32_bf16 v[0:3], v[176:179], v[208:211], v[0:3]
	v_mfma_f32_16x16x32_bf16 v[56:59], v[172:175], v[188:191], v[56:59]
	v_mfma_f32_16x16x32_bf16 v[48:51], v[180:183], v[188:191], v[48:51]
	v_mfma_f32_16x16x32_bf16 v[40:43], v[172:175], v[196:199], v[40:43]
	v_mfma_f32_16x16x32_bf16 v[32:35], v[180:183], v[196:199], v[32:35]
	v_mfma_f32_16x16x32_bf16 v[24:27], v[172:175], v[204:207], v[24:27]
	v_mfma_f32_16x16x32_bf16 v[16:19], v[180:183], v[204:207], v[16:19]
	v_mfma_f32_16x16x32_bf16 v[8:11], v[172:175], v[212:215], v[8:11]
	v_mfma_f32_16x16x32_bf16 v[0:3], v[180:183], v[212:215], v[0:3]
	s_barrier
	s_add_i32 s67, 0, 0x18000
	v_add_u32_e32 v159, s67, v153
	s_add_i32 s68, 0, 0x1c000
	ds_read_b128 v[144:147], v159
	ds_read_b128 v[148:151], v159 offset:1024
	ds_read_b128 v[160:163], v159 offset:2048
	ds_read_b128 v[164:167], v159 offset:3072
	v_add_u32_e32 v159, s68, v153
	ds_read_b128 v[168:171], v159
	ds_read_b128 v[172:175], v159 offset:1024
	ds_read_b128 v[176:179], v159 offset:2048
	ds_read_b128 v[180:183], v159 offset:3072
	s_add_u32 s48, s52, 0x104000
	s_addc_u32 s49, s53, 0
	s_mov_b32 m0, s25
	ds_read_b128 v[184:187], v157 offset:32768
	ds_read_b128 v[188:191], v157 offset:33792
	ds_read_b128 v[192:195], v157 offset:34816
	ds_read_b128 v[196:199], v157 offset:35840
	ds_read_b128 v[200:203], v157 offset:36864
	ds_read_b128 v[204:207], v157 offset:37888
	ds_read_b128 v[208:211], v157 offset:38912
	ds_read_b128 v[212:215], v157 offset:39936
	global_load_lds_dwordx4 v134, s[48:49]
	s_mov_b32 m0, s29
	s_nop 0
	global_load_lds_dwordx4 v130, s[48:49]
	s_mov_b32 m0, s23
	s_nop 0
	global_load_lds_dwordx4 v134, s[52:53]
	s_mov_b32 m0, s24
	s_nop 0
	global_load_lds_dwordx4 v130, s[52:53]
	s_waitcnt vmcnt(8)
	s_waitcnt lgkmcnt(0)
	s_barrier
; #define PG8_STAGE(bufoff, gbase, voff) do { _Pragma("unroll") for (int _i = 0; _i < 2; ++_i) \
;         __builtin_amdgcn_global_load_lds((const unsigned*)((const char*)(gbase) + (voff)[_i]), (PG8_LAS unsigned*)(lds + (bufoff) + ldsw + _i * 8192), 16, 0, 0); } while (0)
; #define PG8_STAGE_NT(bufoff, gbase, voff) do { _Pragma("unroll") for (int _i = 0; _i < 2; ++_i) \
;         __builtin_amdgcn_global_load_lds((const unsigned*)((const char*)(gbase) + (voff)[_i]), (PG8_LAS unsigned*)(lds + (bufoff) + ldsw + _i * 8192), 16, 0, PG8_B_AUX); } while (0)
; #define PG8_LDA(dst, b, h) do { _Pragma("unroll") for (int m = 0; m < 4; ++m) _Pragma("unroll") for (int k = 0; k < 2; ++k) dst[m][k] = *(const PG8_LAS bf16x8*)(lds + PG8_SA(b, h) + aoff + m * 2048 + k * 1024); } while (0)
; #define PG8_LDB(dst, b, h) do { _Pragma("unroll") for (int n = 0; n < 2; ++n) _Pragma("unroll") for (int k = 0; k < 2; ++k) dst[n][k] = *(const PG8_LAS bf16x8*)(lds + PG8_SB(b, h) + boff + n * 2048 + k * 1024); } while (0)
; #define PG8_MMA(ai, bj, At, Bt) do { __builtin_amdgcn_s_setprio(1); _Pragma("unroll") for (int m = 0; m < 4; ++m) _Pragma("unroll") for (int n = 0; n < 2; ++n) _Pragma("unroll") for (int k = 0; k < 2; ++k) \
;         acc[ai][bj][m][n] = __builtin_amdgcn_mfma_f32_16x16x32_bf16(Bt[n][k], At[m][k], acc[ai][bj][m][n], 0, 0, 0); __builtin_amdgcn_s_setprio(0); } while (0)
; #define PG8_WAIT_V(n) asm volatile("s_waitcnt vmcnt(" #n ")" ::: "memory")
; #define PG8_WAIT_L(n) asm volatile("s_waitcnt lgkmcnt(" #n ")" ::: "memory")
; #define PG8_BAR __builtin_amdgcn_s_barrier()
; template <class Epi, class Sched, bool ALIGN_EPI = false, bool SP2 = false>
; __device__ __forceinline__ void gemm_phase(PG8_LAS unsigned char* lds, const Gemm g, const Sched& S, const Epi& E, int wid) {
;     ...
;         for (int t = 0; t < nt; t += 2) {
;     ...
;             PG8_LDB(B0, 1, 0); PG8_LDB(B1, 1, 1); PG8_SCHED; PG8_LDA(At, 1, 0); PG8_STAGE(PG8_SA(0, 1), a2 + hstepA, voffA);
;             PG8_WAIT_V(8); PG8_WAIT_L(0); PG8_BAR; PG8_MMA(0, 0, At, B0); PG8_MMA(0, 1, At, B1); PG8_BAR; PG8_SCHED;
;             PG8_LDA(At, 1, 1); PG8_STAGE_NT(PG8_SB(1, 0), b3, voffB); PG8_STAGE_NT(PG8_SB(1, 1), b3 + hstepB, voffB); PG8_STAGE(PG8_SA(1, 0), a3, voffA);
;             PG8_WAIT_V(8); PG8_WAIT_L(0); PG8_BAR; PG8_MMA(1, 0, At, B0); PG8_MMA(1, 1, At, B1); PG8_BAR; PG8_SCHED;
	s_waitcnt lgkmcnt(0)
	v_mfma_f32_16x16x32_bf16 v[112:115], v[144:147], v[184:187], v[112:115]
	v_mfma_f32_16x16x32_bf16 v[108:111], v[160:163], v[184:187], v[108:111]
	v_mfma_f32_16x16x32_bf16 v[104:107], v[144:147], v[192:195], v[104:107]
	v_mfma_f32_16x16x32_bf16 v[100:103], v[160:163], v[192:195], v[100:103]
	v_mfma_f32_16x16x32_bf16 v[92:95], v[144:147], v[200:203], v[92:95]
	v_mfma_f32_16x16x32_bf16 v[84:87], v[160:163], v[200:203], v[84:87]
	v_mfma_f32_16x16x32_bf16 v[76:79], v[144:147], v[208:211], v[76:79]
	v_mfma_f32_16x16x32_bf16 v[68:71], v[160:163], v[208:211], v[68:71]
	v_mfma_f32_16x16x32_bf16 v[112:115], v[148:151], v[188:191], v[112:115]
	v_mfma_f32_16x16x32_bf16 v[108:111], v[164:167], v[188:191], v[108:111]
	v_mfma_f32_16x16x32_bf16 v[104:107], v[148:151], v[196:199], v[104:107]
	v_mfma_f32_16x16x32_bf16 v[100:103], v[164:167], v[196:199], v[100:103]
	v_mfma_f32_16x16x32_bf16 v[92:95], v[148:151], v[204:207], v[92:95]
	v_mfma_f32_16x16x32_bf16 v[84:87], v[164:167], v[204:207], v[84:87]
	v_mfma_f32_16x16x32_bf16 v[76:79], v[148:151], v[212:215], v[76:79]
	v_mfma_f32_16x16x32_bf16 v[68:71], v[164:167], v[212:215], v[68:71]
	v_mfma_f32_16x16x32_bf16 v[124:127], v[168:171], v[184:187], v[124:127]
	v_mfma_f32_16x16x32_bf16 v[120:123], v[176:179], v[184:187], v[120:123]
	v_mfma_f32_16x16x32_bf16 v[116:119], v[168:171], v[192:195], v[116:119]
	v_mfma_f32_16x16x32_bf16 v[96:99], v[176:179], v[192:195], v[96:99]
	v_mfma_f32_16x16x32_bf16 v[88:91], v[168:171], v[200:203], v[88:91]
	v_mfma_f32_16x16x32_bf16 v[80:83], v[176:179], v[200:203], v[80:83]
	v_mfma_f32_16x16x32_bf16 v[72:75], v[168:171], v[208:211], v[72:75]
	v_mfma_f32_16x16x32_bf16 v[64:67], v[176:179], v[208:211], v[64:67]
	v_mfma_f32_16x16x32_bf16 v[124:127], v[172:175], v[188:191], v[124:127]
	v_mfma_f32_16x16x32_bf16 v[120:123], v[180:183], v[188:191], v[120:123]
	v_mfma_f32_16x16x32_bf16 v[116:119], v[172:175], v[196:199], v[116:119]
	v_mfma_f32_16x16x32_bf16 v[96:99], v[180:183], v[196:199], v[96:99]
	v_mfma_f32_16x16x32_bf16 v[88:91], v[172:175], v[204:207], v[88:91]
	v_mfma_f32_16x16x32_bf16 v[80:83], v[180:183], v[204:207], v[80:83]
	v_mfma_f32_16x16x32_bf16 v[72:75], v[172:175], v[212:215], v[72:75]
	v_mfma_f32_16x16x32_bf16 v[64:67], v[180:183], v[212:215], v[64:67]
	s_barrier
	s_add_i32 s48, s67, s17
	s_mov_b32 m0, s48
	s_add_u32 s98, s50, 0x80
	s_addc_u32 s99, s51, 0
	ds_read_b128 v[184:187], v157 offset:49152
	ds_read_b128 v[188:191], v157 offset:50176
	ds_read_b128 v[192:195], v157 offset:51200
	ds_read_b128 v[196:199], v157 offset:52224
	ds_read_b128 v[200:203], v157 offset:53248
	ds_read_b128 v[204:207], v157 offset:54272
	ds_read_b128 v[208:211], v157 offset:55296
	ds_read_b128 v[212:215], v157 offset:56320
	global_load_lds_dwordx4 v132, s[98:99]
	s_add_i32 m0, s48, 0x2000
	s_add_u32 s48, s50, 0x104080
	s_addc_u32 s49, s51, 0
	s_add_i32 s50, s68, s17
	global_load_lds_dwordx4 v128, s[98:99]
	s_mov_b32 m0, s50
	s_nop 0
	global_load_lds_dwordx4 v132, s[48:49]
	s_add_i32 m0, s50, 0x2000
	s_nop 0
	global_load_lds_dwordx4 v128, s[48:49]
	s_waitcnt vmcnt(4)
	s_waitcnt lgkmcnt(0)
	s_barrier
	s_waitcnt lgkmcnt(0)
	v_mfma_f32_16x16x32_bf16 v[60:63], v[144:147], v[184:187], v[60:63]
	v_mfma_f32_16x16x32_bf16 v[52:55], v[160:163], v[184:187], v[52:55]
	v_mfma_f32_16x16x32_bf16 v[44:47], v[144:147], v[192:195], v[44:47]
	v_mfma_f32_16x16x32_bf16 v[36:39], v[160:163], v[192:195], v[36:39]
	v_mfma_f32_16x16x32_bf16 v[28:31], v[144:147], v[200:203], v[28:31]
	v_mfma_f32_16x16x32_bf16 v[20:23], v[160:163], v[200:203], v[20:23]
	v_mfma_f32_16x16x32_bf16 v[12:15], v[144:147], v[208:211], v[12:15]
	v_mfma_f32_16x16x32_bf16 v[4:7], v[160:163], v[208:211], v[4:7]
	v_mfma_f32_16x16x32_bf16 v[60:63], v[148:151], v[188:191], v[60:63]
	v_mfma_f32_16x16x32_bf16 v[52:55], v[164:167], v[188:191], v[52:55]
	v_mfma_f32_16x16x32_bf16 v[44:47], v[148:151], v[196:199], v[44:47]
	v_mfma_f32_16x16x32_bf16 v[36:39], v[164:167], v[196:199], v[36:39]
	v_mfma_f32_16x16x32_bf16 v[28:31], v[148:151], v[204:207], v[28:31]
	v_mfma_f32_16x16x32_bf16 v[20:23], v[164:167], v[204:207], v[20:23]
	v_mfma_f32_16x16x32_bf16 v[12:15], v[148:151], v[212:215], v[12:15]
	v_mfma_f32_16x16x32_bf16 v[4:7], v[164:167], v[212:215], v[4:7]
	v_mfma_f32_16x16x32_bf16 v[56:59], v[168:171], v[184:187], v[56:59]
	v_mfma_f32_16x16x32_bf16 v[48:51], v[176:179], v[184:187], v[48:51]
	v_mfma_f32_16x16x32_bf16 v[40:43], v[168:171], v[192:195], v[40:43]
	v_mfma_f32_16x16x32_bf16 v[32:35], v[176:179], v[192:195], v[32:35]
	v_mfma_f32_16x16x32_bf16 v[24:27], v[168:171], v[200:203], v[24:27]
	v_mfma_f32_16x16x32_bf16 v[16:19], v[176:179], v[200:203], v[16:19]
	v_mfma_f32_16x16x32_bf16 v[8:11], v[168:171], v[208:211], v[8:11]
	v_mfma_f32_16x16x32_bf16 v[0:3], v[176:179], v[208:211], v[0:3]
	v_mfma_f32_16x16x32_bf16 v[56:59], v[172:175], v[188:191], v[56:59]
	v_mfma_f32_16x16x32_bf16 v[48:51], v[180:183], v[188:191], v[48:51]
	v_mfma_f32_16x16x32_bf16 v[40:43], v[172:175], v[196:199], v[40:43]
	v_mfma_f32_16x16x32_bf16 v[32:35], v[180:183], v[196:199], v[32:35]
	v_mfma_f32_16x16x32_bf16 v[24:27], v[172:175], v[204:207], v[24:27]
	v_mfma_f32_16x16x32_bf16 v[16:19], v[180:183], v[204:207], v[16:19]
	v_mfma_f32_16x16x32_bf16 v[8:11], v[172:175], v[212:215], v[8:11]
	v_mfma_f32_16x16x32_bf16 v[0:3], v[180:183], v[212:215], v[0:3]
	s_add_i32 s66, s66, 2
	s_add_u32 s64, s64, 0x100
	s_addc_u32 s65, s65, 0
	s_cmp_gt_u32 s66, 61
	s_mov_b64 s[48:49], s[4:5]
	s_cbranch_scc0 .Lrot_head_0
	s_barrier
	s_and_b64 vcc, exec, s[42:43]
	s_cbranch_vccz .LBB0_236
	s_barrier

; template <class Epi, class Sched, bool ALIGN_EPI = false, bool SP2 = false>
; __device__ __forceinline__ void gemm_phase(PG8_LAS unsigned char* lds, const Gemm g, const Sched& S, const Epi& E, int wid) {
;     ...
; #pragma unroll
;         for (int a = 0; a < 2; ++a)
; #pragma unroll
;             for (int b = 0; b < 2; ++b)
; #pragma unroll
;                 for (int m = 0; m < 4; ++m)
; #pragma unroll
;                     for (int n = 0; n < 2; ++n) acc[a][b][m][n] = (f32x4){0.f, 0.f, 0.f, 0.f};
.LBB0_316:
	s_add_u32 s62, s48, 0x100
	v_mov_b32_e32 v0, 0
	s_addc_u32 s63, s49, 0
	s_mov_b32 s64, -2
	s_waitcnt lgkmcnt(0)
	v_mov_b32_e32 v1, v0
	v_mov_b32_e32 v2, v0
	v_mov_b32_e32 v3, v0
	v_mov_b32_e32 v4, v0
	v_mov_b32_e32 v5, v0
	v_mov_b32_e32 v6, v0
	v_mov_b32_e32 v7, v0
	v_mov_b32_e32 v16, v0
	v_mov_b32_e32 v17, v0
	v_mov_b32_e32 v18, v0
	v_mov_b32_e32 v19, v0
	v_mov_b32_e32 v20, v0
	v_mov_b32_e32 v21, v0
	v_mov_b32_e32 v22, v0
	v_mov_b32_e32 v23, v0
	v_mov_b32_e32 v32, v0
	v_mov_b32_e32 v33, v0
	v_mov_b32_e32 v34, v0
	v_mov_b32_e32 v35, v0
	v_mov_b32_e32 v36, v0
	v_mov_b32_e32 v37, v0
	v_mov_b32_e32 v38, v0
	v_mov_b32_e32 v39, v0
	v_mov_b32_e32 v48, v0
	v_mov_b32_e32 v49, v0
	v_mov_b32_e32 v50, v0
	v_mov_b32_e32 v51, v0
	v_mov_b32_e32 v52, v0
	v_mov_b32_e32 v53, v0
	v_mov_b32_e32 v54, v0
	v_mov_b32_e32 v55, v0
	v_mov_b32_e32 v8, v0
	v_mov_b32_e32 v9, v0
	v_mov_b32_e32 v10, v0
	v_mov_b32_e32 v11, v0
	v_mov_b32_e32 v12, v0
	v_mov_b32_e32 v13, v0
	v_mov_b32_e32 v14, v0
	v_mov_b32_e32 v15, v0
	v_mov_b32_e32 v24, v0
	v_mov_b32_e32 v25, v0
	v_mov_b32_e32 v26, v0
	v_mov_b32_e32 v27, v0
	v_mov_b32_e32 v28, v0
	v_mov_b32_e32 v29, v0
	v_mov_b32_e32 v30, v0
	v_mov_b32_e32 v31, v0
	v_mov_b32_e32 v40, v0
	v_mov_b32_e32 v41, v0
	v_mov_b32_e32 v42, v0
	v_mov_b32_e32 v43, v0
	v_mov_b32_e32 v44, v0
	v_mov_b32_e32 v45, v0
	v_mov_b32_e32 v46, v0
	v_mov_b32_e32 v47, v0
	v_mov_b32_e32 v56, v0
	v_mov_b32_e32 v57, v0
	v_mov_b32_e32 v58, v0
	v_mov_b32_e32 v59, v0
	v_mov_b32_e32 v60, v0
	v_mov_b32_e32 v61, v0
	v_mov_b32_e32 v62, v0
	v_mov_b32_e32 v63, v0
	v_mov_b32_e32 v64, v0
	v_mov_b32_e32 v65, v0
	v_mov_b32_e32 v66, v0
	v_mov_b32_e32 v67, v0
	v_mov_b32_e32 v68, v0
	v_mov_b32_e32 v69, v0
	v_mov_b32_e32 v70, v0
	v_mov_b32_e32 v71, v0
	v_mov_b32_e32 v80, v0
	v_mov_b32_e32 v81, v0
	v_mov_b32_e32 v82, v0
	v_mov_b32_e32 v83, v0
	v_mov_b32_e32 v84, v0
	v_mov_b32_e32 v85, v0
	v_mov_b32_e32 v86, v0
	v_mov_b32_e32 v87, v0
	v_mov_b32_e32 v96, v0
	v_mov_b32_e32 v97, v0
	v_mov_b32_e32 v98, v0
	v_mov_b32_e32 v99, v0
	v_mov_b32_e32 v100, v0
	v_mov_b32_e32 v101, v0
	v_mov_b32_e32 v102, v0
	v_mov_b32_e32 v103, v0
	v_mov_b32_e32 v104, v0
	v_mov_b32_e32 v105, v0
	v_mov_b32_e32 v106, v0
	v_mov_b32_e32 v107, v0
	v_mov_b32_e32 v108, v0
	v_mov_b32_e32 v109, v0
	v_mov_b32_e32 v110, v0
	v_mov_b32_e32 v111, v0
	v_mov_b32_e32 v72, v0
	v_mov_b32_e32 v73, v0
	v_mov_b32_e32 v74, v0
	v_mov_b32_e32 v75, v0
	v_mov_b32_e32 v76, v0
	v_mov_b32_e32 v77, v0
	v_mov_b32_e32 v78, v0
	v_mov_b32_e32 v79, v0
	v_mov_b32_e32 v88, v0
	v_mov_b32_e32 v89, v0
	v_mov_b32_e32 v90, v0
	v_mov_b32_e32 v91, v0
	v_mov_b32_e32 v92, v0
	v_mov_b32_e32 v93, v0
	v_mov_b32_e32 v94, v0
	v_mov_b32_e32 v95, v0
	v_mov_b32_e32 v112, v0
	v_mov_b32_e32 v113, v0
	v_mov_b32_e32 v114, v0
	v_mov_b32_e32 v115, v0
	v_mov_b32_e32 v116, v0
	v_mov_b32_e32 v117, v0
	v_mov_b32_e32 v118, v0
	v_mov_b32_e32 v119, v0
	v_mov_b32_e32 v120, v0
	v_mov_b32_e32 v121, v0
	v_mov_b32_e32 v122, v0
	v_mov_b32_e32 v123, v0
	v_mov_b32_e32 v124, v0
	v_mov_b32_e32 v125, v0
	v_mov_b32_e32 v126, v0
	v_mov_b32_e32 v127, v0
	s_branch .LBB0_317

; #define PG8_STAGE(bufoff, gbase, voff) do { _Pragma("unroll") for (int _i = 0; _i < 2; ++_i) \
;         __builtin_amdgcn_global_load_lds((const unsigned*)((const char*)(gbase) + (voff)[_i]), (PG8_LAS unsigned*)(lds + (bufoff) + ldsw + _i * 8192), 16, 0, 0); } while (0)
; #define PG8_STAGE_NT(bufoff, gbase, voff) do { _Pragma("unroll") for (int _i = 0; _i < 2; ++_i) \
;         __builtin_amdgcn_global_load_lds((const unsigned*)((const char*)(gbase) + (voff)[_i]), (PG8_LAS unsigned*)(lds + (bufoff) + ldsw + _i * 8192), 16, 0, PG8_B_AUX); } while (0)
; #define PG8_LDA(dst, b, h) do { _Pragma("unroll") for (int m = 0; m < 4; ++m) _Pragma("unroll") for (int k = 0; k < 2; ++k) dst[m][k] = *(const PG8_LAS bf16x8*)(lds + PG8_SA(b, h) + aoff + m * 2048 + k * 1024); } while (0)
; #define PG8_LDB(dst, b, h) do { _Pragma("unroll") for (int n = 0; n < 2; ++n) _Pragma("unroll") for (int k = 0; k < 2; ++k) dst[n][k] = *(const PG8_LAS bf16x8*)(lds + PG8_SB(b, h) + boff + n * 2048 + k * 1024); } while (0)
; #define PG8_MMA(ai, bj, At, Bt) do { __builtin_amdgcn_s_setprio(1); _Pragma("unroll") for (int m = 0; m < 4; ++m) _Pragma("unroll") for (int n = 0; n < 2; ++n) _Pragma("unroll") for (int k = 0; k < 2; ++k) \
;         acc[ai][bj][m][n] = __builtin_amdgcn_mfma_f32_16x16x32_bf16(Bt[n][k], At[m][k], acc[ai][bj][m][n], 0, 0, 0); __builtin_amdgcn_s_setprio(0); } while (0)
; #define PG8_WAIT_V(n) asm volatile("s_waitcnt vmcnt(" #n ")" ::: "memory")
; #define PG8_WAIT_L(n) asm volatile("s_waitcnt lgkmcnt(" #n ")" ::: "memory")
; #define PG8_BAR __builtin_amdgcn_s_barrier()
; #define PG8_SCHED __builtin_amdgcn_sched_barrier(0)
; template <class Epi, class Sched, bool ALIGN_EPI = false, bool SP2 = false>
; __device__ __forceinline__ void gemm_phase(PG8_LAS unsigned char* lds, const Gemm g, const Sched& S, const Epi& E, int wid) {
;     ...
;             PG8_LDB(B0, 0, 0); PG8_LDB(B1, 0, 1); PG8_SCHED; PG8_LDA(At, 0, 0); PG8_STAGE(PG8_SA(1, 1), a1 + hstepA, voffA);
;             PG8_WAIT_V(8); PG8_WAIT_L(0); PG8_BAR; PG8_MMA(0, 0, At, B0); PG8_MMA(0, 1, At, B1); PG8_BAR; PG8_SCHED;
;             PG8_LDA(At, 0, 1); PG8_STAGE_NT(PG8_SB(0, 0), b2, voffB); PG8_STAGE_NT(PG8_SB(0, 1), b2 + hstepB, voffB); PG8_STAGE(PG8_SA(0, 0), a2, voffA);
;             PG8_WAIT_V(8); PG8_WAIT_L(0); PG8_BAR; PG8_MMA(1, 0, At, B0); PG8_MMA(1, 1, At, B1); PG8_BAR; PG8_SCHED;
.LBB0_317:
	ds_read_b128 v[128:131], v205
	ds_read_b128 v[132:135], v205 offset:1024
	ds_read_b128 v[136:139], v205 offset:2048
	ds_read_b128 v[140:143], v205 offset:3072
	ds_read_b128 v[144:147], v206
	ds_read_b128 v[148:151], v206 offset:1024
	ds_read_b128 v[152:155], v206 offset:2048
	ds_read_b128 v[156:159], v206 offset:3072
	s_add_u32 s48, s46, 0x100
	s_addc_u32 s49, s47, 0
	s_add_u32 s98, s46, 0x80
	s_addc_u32 s99, s47, 0
	s_add_u32 s100, s46, 0x2b4080
	s_addc_u32 s101, s47, 0
	s_cmpk_eq_i32 s64, 0xa8
	s_cselect_b32 s53, s7, s49
	s_cselect_b32 s52, s6, s48
	s_cselect_b32 s51, s45, s63
	s_cselect_b32 s50, s44, s62
	s_add_i32 m0, s19, 0xc000
	ds_read_b128 v[160:163], v207
	ds_read_b128 v[164:167], v207 offset:1024
	ds_read_b128 v[184:187], v207 offset:2048
	ds_read_b128 v[188:191], v207 offset:3072
	ds_read_b128 v[192:195], v207 offset:4096
	ds_read_b128 v[196:199], v207 offset:5120
	ds_read_b128 v[210:213], v207 offset:6144
	ds_read_b128 v[214:217], v207 offset:7168
	global_load_lds_dwordx4 v168, s[100:101]
	s_add_i32 m0, s19, 0xe000
	s_nop 0
	global_load_lds_dwordx4 v172, s[100:101]
	s_mov_b32 m0, s29
	s_nop 0
	global_load_lds_dwordx4 v168, s[98:99]
	s_mov_b32 m0, s54
	s_nop 0
	global_load_lds_dwordx4 v172, s[98:99]
	s_waitcnt vmcnt(8)
	s_waitcnt lgkmcnt(0)
	s_barrier
	s_waitcnt lgkmcnt(0)
	v_mfma_f32_16x16x32_bf16 v[124:127], v[128:131], v[160:163], v[124:127]
	v_mfma_f32_16x16x32_bf16 v[120:123], v[136:139], v[160:163], v[120:123]
	v_mfma_f32_16x16x32_bf16 v[116:119], v[128:131], v[184:187], v[116:119]
	v_mfma_f32_16x16x32_bf16 v[112:115], v[136:139], v[184:187], v[112:115]
	v_mfma_f32_16x16x32_bf16 v[92:95], v[128:131], v[192:195], v[92:95]
	v_mfma_f32_16x16x32_bf16 v[88:91], v[136:139], v[192:195], v[88:91]
	v_mfma_f32_16x16x32_bf16 v[76:79], v[128:131], v[210:213], v[76:79]
	v_mfma_f32_16x16x32_bf16 v[72:75], v[136:139], v[210:213], v[72:75]
	v_mfma_f32_16x16x32_bf16 v[124:127], v[132:135], v[164:167], v[124:127]
	v_mfma_f32_16x16x32_bf16 v[120:123], v[140:143], v[164:167], v[120:123]
	v_mfma_f32_16x16x32_bf16 v[116:119], v[132:135], v[188:191], v[116:119]
	v_mfma_f32_16x16x32_bf16 v[112:115], v[140:143], v[188:191], v[112:115]
	v_mfma_f32_16x16x32_bf16 v[92:95], v[132:135], v[196:199], v[92:95]
	v_mfma_f32_16x16x32_bf16 v[88:91], v[140:143], v[196:199], v[88:91]
	v_mfma_f32_16x16x32_bf16 v[76:79], v[132:135], v[214:217], v[76:79]
	v_mfma_f32_16x16x32_bf16 v[72:75], v[140:143], v[214:217], v[72:75]
	v_mfma_f32_16x16x32_bf16 v[108:111], v[144:147], v[160:163], v[108:111]
	v_mfma_f32_16x16x32_bf16 v[104:107], v[152:155], v[160:163], v[104:107]
	v_mfma_f32_16x16x32_bf16 v[100:103], v[144:147], v[184:187], v[100:103]
	v_mfma_f32_16x16x32_bf16 v[96:99], v[152:155], v[184:187], v[96:99]
	v_mfma_f32_16x16x32_bf16 v[84:87], v[144:147], v[192:195], v[84:87]
	v_mfma_f32_16x16x32_bf16 v[80:83], v[152:155], v[192:195], v[80:83]
	v_mfma_f32_16x16x32_bf16 v[68:71], v[144:147], v[210:213], v[68:71]
	v_mfma_f32_16x16x32_bf16 v[64:67], v[152:155], v[210:213], v[64:67]
	v_mfma_f32_16x16x32_bf16 v[108:111], v[148:151], v[164:167], v[108:111]
	v_mfma_f32_16x16x32_bf16 v[104:107], v[156:159], v[164:167], v[104:107]
	v_mfma_f32_16x16x32_bf16 v[100:103], v[148:151], v[188:191], v[100:103]
	v_mfma_f32_16x16x32_bf16 v[96:99], v[156:159], v[188:191], v[96:99]
	v_mfma_f32_16x16x32_bf16 v[84:87], v[148:151], v[196:199], v[84:87]
	v_mfma_f32_16x16x32_bf16 v[80:83], v[156:159], v[196:199], v[80:83]
	v_mfma_f32_16x16x32_bf16 v[68:71], v[148:151], v[214:217], v[68:71]
	v_mfma_f32_16x16x32_bf16 v[64:67], v[156:159], v[214:217], v[64:67]
	s_barrier
	s_add_i32 s46, s57, s17
	s_mov_b32 m0, s46
	ds_read_b128 v[160:163], v207 offset:16384
	ds_read_b128 v[164:167], v207 offset:17408
	ds_read_b128 v[184:187], v207 offset:18432
	ds_read_b128 v[188:191], v207 offset:19456
	ds_read_b128 v[192:195], v207 offset:20480
	ds_read_b128 v[196:199], v207 offset:21504
	ds_read_b128 v[210:213], v207 offset:22528
	ds_read_b128 v[214:217], v207 offset:23552
	global_load_lds_dwordx4 v170, s[50:51]
	s_add_i32 m0, s46, 0x2000
	s_add_u32 s46, s50, 0x2b4000
	s_addc_u32 s47, s51, 0
	s_add_i32 s65, s58, s17
	global_load_lds_dwordx4 v174, s[50:51]
	s_mov_b32 m0, s65
	s_nop 0
	global_load_lds_dwordx4 v170, s[46:47]
	s_add_i32 m0, s65, 0x2000
	s_nop 0
	global_load_lds_dwordx4 v174, s[46:47]
	s_waitcnt vmcnt(4)
	s_waitcnt lgkmcnt(0)
	s_barrier
	s_waitcnt lgkmcnt(0)
	v_mfma_f32_16x16x32_bf16 v[60:63], v[128:131], v[160:163], v[60:63]
	v_mfma_f32_16x16x32_bf16 v[56:59], v[136:139], v[160:163], v[56:59]
	v_mfma_f32_16x16x32_bf16 v[44:47], v[128:131], v[184:187], v[44:47]
	v_mfma_f32_16x16x32_bf16 v[40:43], v[136:139], v[184:187], v[40:43]
	v_mfma_f32_16x16x32_bf16 v[28:31], v[128:131], v[192:195], v[28:31]
	v_mfma_f32_16x16x32_bf16 v[24:27], v[136:139], v[192:195], v[24:27]
	v_mfma_f32_16x16x32_bf16 v[12:15], v[128:131], v[210:213], v[12:15]
	v_mfma_f32_16x16x32_bf16 v[8:11], v[136:139], v[210:213], v[8:11]
	v_mfma_f32_16x16x32_bf16 v[60:63], v[132:135], v[164:167], v[60:63]
	v_mfma_f32_16x16x32_bf16 v[56:59], v[140:143], v[164:167], v[56:59]
	v_mfma_f32_16x16x32_bf16 v[44:47], v[132:135], v[188:191], v[44:47]
	v_mfma_f32_16x16x32_bf16 v[40:43], v[140:143], v[188:191], v[40:43]
	v_mfma_f32_16x16x32_bf16 v[28:31], v[132:135], v[196:199], v[28:31]
	v_mfma_f32_16x16x32_bf16 v[24:27], v[140:143], v[196:199], v[24:27]
	v_mfma_f32_16x16x32_bf16 v[12:15], v[132:135], v[214:217], v[12:15]
	v_mfma_f32_16x16x32_bf16 v[8:11], v[140:143], v[214:217], v[8:11]
	v_mfma_f32_16x16x32_bf16 v[52:55], v[144:147], v[160:163], v[52:55]
	v_mfma_f32_16x16x32_bf16 v[48:51], v[152:155], v[160:163], v[48:51]
	v_mfma_f32_16x16x32_bf16 v[36:39], v[144:147], v[184:187], v[36:39]
	v_mfma_f32_16x16x32_bf16 v[32:35], v[152:155], v[184:187], v[32:35]
	v_mfma_f32_16x16x32_bf16 v[20:23], v[144:147], v[192:195], v[20:23]
	v_mfma_f32_16x16x32_bf16 v[16:19], v[152:155], v[192:195], v[16:19]
	v_mfma_f32_16x16x32_bf16 v[4:7], v[144:147], v[210:213], v[4:7]
	v_mfma_f32_16x16x32_bf16 v[0:3], v[152:155], v[210:213], v[0:3]
	v_mfma_f32_16x16x32_bf16 v[52:55], v[148:151], v[164:167], v[52:55]
	v_mfma_f32_16x16x32_bf16 v[48:51], v[156:159], v[164:167], v[48:51]
	v_mfma_f32_16x16x32_bf16 v[36:39], v[148:151], v[188:191], v[36:39]
	v_mfma_f32_16x16x32_bf16 v[32:35], v[156:159], v[188:191], v[32:35]
	v_mfma_f32_16x16x32_bf16 v[20:23], v[148:151], v[196:199], v[20:23]
	v_mfma_f32_16x16x32_bf16 v[16:19], v[156:159], v[196:199], v[16:19]
	v_mfma_f32_16x16x32_bf16 v[4:7], v[148:151], v[214:217], v[4:7]
	v_mfma_f32_16x16x32_bf16 v[0:3], v[156:159], v[214:217], v[0:3]
	s_barrier
; #define PG8_STAGE(bufoff, gbase, voff) do { _Pragma("unroll") for (int _i = 0; _i < 2; ++_i) \
;         __builtin_amdgcn_global_load_lds((const unsigned*)((const char*)(gbase) + (voff)[_i]), (PG8_LAS unsigned*)(lds + (bufoff) + ldsw + _i * 8192), 16, 0, 0); } while (0)
; #define PG8_STAGE_NT(bufoff, gbase, voff) do { _Pragma("unroll") for (int _i = 0; _i < 2; ++_i) \
;         __builtin_amdgcn_global_load_lds((const unsigned*)((const char*)(gbase) + (voff)[_i]), (PG8_LAS unsigned*)(lds + (bufoff) + ldsw + _i * 8192), 16, 0, PG8_B_AUX); } while (0)
; #define PG8_LDA(dst, b, h) do { _Pragma("unroll") for (int m = 0; m < 4; ++m) _Pragma("unroll") for (int k = 0; k < 2; ++k) dst[m][k] = *(const PG8_LAS bf16x8*)(lds + PG8_SA(b, h) + aoff + m * 2048 + k * 1024); } while (0)
; #define PG8_LDB(dst, b, h) do { _Pragma("unroll") for (int n = 0; n < 2; ++n) _Pragma("unroll") for (int k = 0; k < 2; ++k) dst[n][k] = *(const PG8_LAS bf16x8*)(lds + PG8_SB(b, h) + boff + n * 2048 + k * 1024); } while (0)
; #define PG8_MMA(ai, bj, At, Bt) do { __builtin_amdgcn_s_setprio(1); _Pragma("unroll") for (int m = 0; m < 4; ++m) _Pragma("unroll") for (int n = 0; n < 2; ++n) _Pragma("unroll") for (int k = 0; k < 2; ++k) \
;         acc[ai][bj][m][n] = __builtin_amdgcn_mfma_f32_16x16x32_bf16(Bt[n][k], At[m][k], acc[ai][bj][m][n], 0, 0, 0); __builtin_amdgcn_s_setprio(0); } while (0)
; #define PG8_WAIT_V(n) asm volatile("s_waitcnt vmcnt(" #n ")" ::: "memory")
; #define PG8_WAIT_L(n) asm volatile("s_waitcnt lgkmcnt(" #n ")" ::: "memory")
; #define PG8_BAR __builtin_amdgcn_s_barrier()
; #define PG8_SCHED __builtin_amdgcn_sched_barrier(0)
; template <class Epi, class Sched, bool ALIGN_EPI = false, bool SP2 = false>
; __device__ __forceinline__ void gemm_phase(PG8_LAS unsigned char* lds, const Gemm g, const Sched& S, const Epi& E, int wid) {
;     ...
;             PG8_LDB(B0, 1, 0); PG8_LDB(B1, 1, 1); PG8_SCHED; PG8_LDA(At, 1, 0); PG8_STAGE(PG8_SA(0, 1), a2 + hstepA, voffA);
;             PG8_WAIT_V(8); PG8_WAIT_L(0); PG8_BAR; PG8_MMA(0, 0, At, B0); PG8_MMA(0, 1, At, B1); PG8_BAR; PG8_SCHED;
;             PG8_LDA(At, 1, 1); PG8_STAGE_NT(PG8_SB(1, 0), b3, voffB); PG8_STAGE_NT(PG8_SB(1, 1), b3 + hstepB, voffB); PG8_STAGE(PG8_SA(1, 0), a3, voffA);
;             PG8_WAIT_V(8); PG8_WAIT_L(0); PG8_BAR; PG8_MMA(1, 0, At, B0); PG8_MMA(1, 1, At, B1); PG8_BAR; PG8_SCHED;
	s_add_i32 s65, 0, 0x18000
	v_add_u32_e32 v140, s65, v203
	s_add_i32 s66, 0, 0x1c000
	ds_read_b128 v[128:131], v140
	ds_read_b128 v[132:135], v140 offset:1024
	ds_read_b128 v[136:139], v140 offset:2048
	ds_read_b128 v[140:143], v140 offset:3072
	v_add_u32_e32 v156, s66, v203
	ds_read_b128 v[144:147], v156
	ds_read_b128 v[148:151], v156 offset:1024
	ds_read_b128 v[152:155], v156 offset:2048
	ds_read_b128 v[156:159], v156 offset:3072
	s_add_u32 s46, s52, 0x2b4000
	s_addc_u32 s47, s53, 0
	s_mov_b32 m0, s23
	ds_read_b128 v[160:163], v207 offset:32768
	ds_read_b128 v[164:167], v207 offset:33792
	ds_read_b128 v[184:187], v207 offset:34816
	ds_read_b128 v[188:191], v207 offset:35840
	ds_read_b128 v[192:195], v207 offset:36864
	ds_read_b128 v[196:199], v207 offset:37888
	ds_read_b128 v[210:213], v207 offset:38912
	ds_read_b128 v[214:217], v207 offset:39936
	global_load_lds_dwordx4 v168, s[46:47]
	s_mov_b32 m0, s24
	s_nop 0
	global_load_lds_dwordx4 v172, s[46:47]
	s_mov_b32 m0, s19
	s_nop 0
	global_load_lds_dwordx4 v168, s[52:53]
	s_mov_b32 m0, s22
	s_nop 0
	global_load_lds_dwordx4 v172, s[52:53]
	s_waitcnt vmcnt(8)
	s_waitcnt lgkmcnt(0)
	s_barrier
	s_waitcnt lgkmcnt(0)
	v_mfma_f32_16x16x32_bf16 v[124:127], v[128:131], v[160:163], v[124:127]
	v_mfma_f32_16x16x32_bf16 v[120:123], v[136:139], v[160:163], v[120:123]
	v_mfma_f32_16x16x32_bf16 v[116:119], v[128:131], v[184:187], v[116:119]
	v_mfma_f32_16x16x32_bf16 v[112:115], v[136:139], v[184:187], v[112:115]
	v_mfma_f32_16x16x32_bf16 v[92:95], v[128:131], v[192:195], v[92:95]
	v_mfma_f32_16x16x32_bf16 v[88:91], v[136:139], v[192:195], v[88:91]
	v_mfma_f32_16x16x32_bf16 v[76:79], v[128:131], v[210:213], v[76:79]
	v_mfma_f32_16x16x32_bf16 v[72:75], v[136:139], v[210:213], v[72:75]
	v_mfma_f32_16x16x32_bf16 v[124:127], v[132:135], v[164:167], v[124:127]
	v_mfma_f32_16x16x32_bf16 v[120:123], v[140:143], v[164:167], v[120:123]
	v_mfma_f32_16x16x32_bf16 v[116:119], v[132:135], v[188:191], v[116:119]
	v_mfma_f32_16x16x32_bf16 v[112:115], v[140:143], v[188:191], v[112:115]
	v_mfma_f32_16x16x32_bf16 v[92:95], v[132:135], v[196:199], v[92:95]
	v_mfma_f32_16x16x32_bf16 v[88:91], v[140:143], v[196:199], v[88:91]
	v_mfma_f32_16x16x32_bf16 v[76:79], v[132:135], v[214:217], v[76:79]
	v_mfma_f32_16x16x32_bf16 v[72:75], v[140:143], v[214:217], v[72:75]
	v_mfma_f32_16x16x32_bf16 v[108:111], v[144:147], v[160:163], v[108:111]
	v_mfma_f32_16x16x32_bf16 v[104:107], v[152:155], v[160:163], v[104:107]
	v_mfma_f32_16x16x32_bf16 v[100:103], v[144:147], v[184:187], v[100:103]
	v_mfma_f32_16x16x32_bf16 v[96:99], v[152:155], v[184:187], v[96:99]
	v_mfma_f32_16x16x32_bf16 v[84:87], v[144:147], v[192:195], v[84:87]
	v_mfma_f32_16x16x32_bf16 v[80:83], v[152:155], v[192:195], v[80:83]
	v_mfma_f32_16x16x32_bf16 v[68:71], v[144:147], v[210:213], v[68:71]
	v_mfma_f32_16x16x32_bf16 v[64:67], v[152:155], v[210:213], v[64:67]
	v_mfma_f32_16x16x32_bf16 v[108:111], v[148:151], v[164:167], v[108:111]
	v_mfma_f32_16x16x32_bf16 v[104:107], v[156:159], v[164:167], v[104:107]
	v_mfma_f32_16x16x32_bf16 v[100:103], v[148:151], v[188:191], v[100:103]
	v_mfma_f32_16x16x32_bf16 v[96:99], v[156:159], v[188:191], v[96:99]
	v_mfma_f32_16x16x32_bf16 v[84:87], v[148:151], v[196:199], v[84:87]
	v_mfma_f32_16x16x32_bf16 v[80:83], v[156:159], v[196:199], v[80:83]
	v_mfma_f32_16x16x32_bf16 v[68:71], v[148:151], v[214:217], v[68:71]
	v_mfma_f32_16x16x32_bf16 v[64:67], v[156:159], v[214:217], v[64:67]
	s_barrier
	s_add_i32 s46, s65, s17
	s_mov_b32 m0, s46
	s_add_u32 s98, s50, 0x80
	s_addc_u32 s99, s51, 0
	ds_read_b128 v[160:163], v207 offset:49152
	ds_read_b128 v[164:167], v207 offset:50176
	ds_read_b128 v[184:187], v207 offset:51200
	ds_read_b128 v[188:191], v207 offset:52224
	ds_read_b128 v[192:195], v207 offset:53248
	ds_read_b128 v[196:199], v207 offset:54272
	ds_read_b128 v[210:213], v207 offset:55296
	ds_read_b128 v[214:217], v207 offset:56320
	global_load_lds_dwordx4 v170, s[98:99]
	s_add_i32 m0, s46, 0x2000
	s_add_u32 s46, s50, 0x2b4080
	s_addc_u32 s47, s51, 0
	s_add_i32 s50, s66, s17
	global_load_lds_dwordx4 v174, s[98:99]
	s_mov_b32 m0, s50
	s_nop 0
	global_load_lds_dwordx4 v170, s[46:47]
	s_add_i32 m0, s50, 0x2000
	s_nop 0
	global_load_lds_dwordx4 v174, s[46:47]
	s_waitcnt vmcnt(4)
	s_waitcnt lgkmcnt(0)
	s_barrier
	s_waitcnt lgkmcnt(0)
	v_mfma_f32_16x16x32_bf16 v[60:63], v[128:131], v[160:163], v[60:63]
	v_mfma_f32_16x16x32_bf16 v[56:59], v[136:139], v[160:163], v[56:59]
	v_mfma_f32_16x16x32_bf16 v[44:47], v[128:131], v[184:187], v[44:47]
	v_mfma_f32_16x16x32_bf16 v[40:43], v[136:139], v[184:187], v[40:43]
	v_mfma_f32_16x16x32_bf16 v[28:31], v[128:131], v[192:195], v[28:31]
	v_mfma_f32_16x16x32_bf16 v[24:27], v[136:139], v[192:195], v[24:27]
	v_mfma_f32_16x16x32_bf16 v[12:15], v[128:131], v[210:213], v[12:15]
	v_mfma_f32_16x16x32_bf16 v[8:11], v[136:139], v[210:213], v[8:11]
	v_mfma_f32_16x16x32_bf16 v[60:63], v[132:135], v[164:167], v[60:63]
	v_mfma_f32_16x16x32_bf16 v[56:59], v[140:143], v[164:167], v[56:59]
	v_mfma_f32_16x16x32_bf16 v[44:47], v[132:135], v[188:191], v[44:47]
	v_mfma_f32_16x16x32_bf16 v[40:43], v[140:143], v[188:191], v[40:43]
	v_mfma_f32_16x16x32_bf16 v[28:31], v[132:135], v[196:199], v[28:31]
	v_mfma_f32_16x16x32_bf16 v[24:27], v[140:143], v[196:199], v[24:27]
	v_mfma_f32_16x16x32_bf16 v[12:15], v[132:135], v[214:217], v[12:15]
	v_mfma_f32_16x16x32_bf16 v[8:11], v[140:143], v[214:217], v[8:11]
	v_mfma_f32_16x16x32_bf16 v[52:55], v[144:147], v[160:163], v[52:55]
	v_mfma_f32_16x16x32_bf16 v[48:51], v[152:155], v[160:163], v[48:51]
	v_mfma_f32_16x16x32_bf16 v[36:39], v[144:147], v[184:187], v[36:39]
	v_mfma_f32_16x16x32_bf16 v[32:35], v[152:155], v[184:187], v[32:35]
	v_mfma_f32_16x16x32_bf16 v[20:23], v[144:147], v[192:195], v[20:23]
	v_mfma_f32_16x16x32_bf16 v[16:19], v[152:155], v[192:195], v[16:19]
	v_mfma_f32_16x16x32_bf16 v[4:7], v[144:147], v[210:213], v[4:7]
	v_mfma_f32_16x16x32_bf16 v[0:3], v[152:155], v[210:213], v[0:3]
	v_mfma_f32_16x16x32_bf16 v[52:55], v[148:151], v[164:167], v[52:55]
	v_mfma_f32_16x16x32_bf16 v[48:51], v[156:159], v[164:167], v[48:51]
	v_mfma_f32_16x16x32_bf16 v[36:39], v[148:151], v[188:191], v[36:39]
	v_mfma_f32_16x16x32_bf16 v[32:35], v[156:159], v[188:191], v[32:35]
	v_mfma_f32_16x16x32_bf16 v[20:23], v[148:151], v[196:199], v[20:23]
	v_mfma_f32_16x16x32_bf16 v[16:19], v[156:159], v[196:199], v[16:19]
	v_mfma_f32_16x16x32_bf16 v[4:7], v[148:151], v[214:217], v[4:7]
	v_mfma_f32_16x16x32_bf16 v[0:3], v[156:159], v[214:217], v[0:3]
	s_add_i32 s64, s64, 2
	s_add_u32 s62, s62, 0x100
	s_addc_u32 s63, s63, 0
	s_cmpk_gt_u32 s64, 0xa9
	s_mov_b64 s[46:47], s[48:49]
	s_cbranch_scc0 .Lrot_head_1
	s_barrier
	s_and_b64 vcc, exec, s[42:43]
	s_cbranch_vccz .LBB0_320
	s_barrier

; template <class Epi, class Sched, bool ALIGN_EPI = false, bool SP2 = false>
; __device__ __forceinline__ void gemm_phase(PG8_LAS unsigned char* lds, const Gemm g, const Sched& S, const Epi& E, int wid) {
;     ...
; #pragma unroll
;         for (int a = 0; a < 2; ++a)
; #pragma unroll
;             for (int b = 0; b < 2; ++b)
; #pragma unroll
;                 for (int m = 0; m < 4; ++m)
; #pragma unroll
;                     for (int n = 0; n < 2; ++n) acc[a][b][m][n] = (f32x4){0.f, 0.f, 0.f, 0.f};
.LBB0_425:
	s_add_u32 s62, s48, 0x100
	v_mov_b32_e32 v0, 0
	s_addc_u32 s63, s49, 0
	s_mov_b32 s64, -2
	v_mov_b32_e32 v1, v0
	v_mov_b32_e32 v2, v0
	v_mov_b32_e32 v3, v0
	v_mov_b32_e32 v4, v0
	v_mov_b32_e32 v5, v0
	v_mov_b32_e32 v6, v0
	v_mov_b32_e32 v7, v0
	v_mov_b32_e32 v16, v0
	v_mov_b32_e32 v17, v0
	v_mov_b32_e32 v18, v0
	v_mov_b32_e32 v19, v0
	v_mov_b32_e32 v20, v0
	v_mov_b32_e32 v21, v0
	v_mov_b32_e32 v22, v0
	v_mov_b32_e32 v23, v0
	v_mov_b32_e32 v32, v0
	v_mov_b32_e32 v33, v0
	v_mov_b32_e32 v34, v0
	v_mov_b32_e32 v35, v0
	v_mov_b32_e32 v36, v0
	v_mov_b32_e32 v37, v0
	v_mov_b32_e32 v38, v0
	v_mov_b32_e32 v39, v0
	v_mov_b32_e32 v48, v0
	v_mov_b32_e32 v49, v0
	v_mov_b32_e32 v50, v0
	v_mov_b32_e32 v51, v0
	v_mov_b32_e32 v52, v0
	v_mov_b32_e32 v53, v0
	v_mov_b32_e32 v54, v0
	v_mov_b32_e32 v55, v0
	v_mov_b32_e32 v8, v0
	v_mov_b32_e32 v9, v0
	v_mov_b32_e32 v10, v0
	v_mov_b32_e32 v11, v0
	v_mov_b32_e32 v12, v0
	v_mov_b32_e32 v13, v0
	v_mov_b32_e32 v14, v0
	v_mov_b32_e32 v15, v0
	v_mov_b32_e32 v24, v0
	v_mov_b32_e32 v25, v0
	v_mov_b32_e32 v26, v0
	v_mov_b32_e32 v27, v0
	v_mov_b32_e32 v28, v0
	v_mov_b32_e32 v29, v0
	v_mov_b32_e32 v30, v0
	v_mov_b32_e32 v31, v0
	v_mov_b32_e32 v40, v0
	v_mov_b32_e32 v41, v0
	v_mov_b32_e32 v42, v0
	v_mov_b32_e32 v43, v0
	v_mov_b32_e32 v44, v0
	v_mov_b32_e32 v45, v0
	v_mov_b32_e32 v46, v0
	v_mov_b32_e32 v47, v0
	v_mov_b32_e32 v56, v0
	v_mov_b32_e32 v57, v0
	v_mov_b32_e32 v58, v0
	v_mov_b32_e32 v59, v0
	v_mov_b32_e32 v60, v0
	v_mov_b32_e32 v61, v0
	v_mov_b32_e32 v62, v0
	v_mov_b32_e32 v63, v0
	v_mov_b32_e32 v64, v0
	v_mov_b32_e32 v65, v0
	v_mov_b32_e32 v66, v0
	v_mov_b32_e32 v67, v0
	v_mov_b32_e32 v68, v0
	v_mov_b32_e32 v69, v0
	v_mov_b32_e32 v70, v0
	v_mov_b32_e32 v71, v0
	v_mov_b32_e32 v80, v0
	v_mov_b32_e32 v81, v0
	v_mov_b32_e32 v82, v0
	v_mov_b32_e32 v83, v0
	v_mov_b32_e32 v84, v0
	v_mov_b32_e32 v85, v0
	v_mov_b32_e32 v86, v0
	v_mov_b32_e32 v87, v0
	v_mov_b32_e32 v96, v0
	v_mov_b32_e32 v97, v0
	v_mov_b32_e32 v98, v0
	v_mov_b32_e32 v99, v0
	v_mov_b32_e32 v100, v0
	v_mov_b32_e32 v101, v0
	v_mov_b32_e32 v102, v0
	v_mov_b32_e32 v103, v0
	v_mov_b32_e32 v104, v0
	v_mov_b32_e32 v105, v0
	v_mov_b32_e32 v106, v0
	v_mov_b32_e32 v107, v0
	v_mov_b32_e32 v108, v0
	v_mov_b32_e32 v109, v0
	v_mov_b32_e32 v110, v0
	v_mov_b32_e32 v111, v0
	v_mov_b32_e32 v72, v0
	v_mov_b32_e32 v73, v0
	v_mov_b32_e32 v74, v0
	v_mov_b32_e32 v75, v0
	v_mov_b32_e32 v76, v0
	v_mov_b32_e32 v77, v0
	v_mov_b32_e32 v78, v0
	v_mov_b32_e32 v79, v0
	v_mov_b32_e32 v88, v0
	v_mov_b32_e32 v89, v0
	v_mov_b32_e32 v90, v0
	v_mov_b32_e32 v91, v0
	v_mov_b32_e32 v92, v0
	v_mov_b32_e32 v93, v0
	v_mov_b32_e32 v94, v0
	v_mov_b32_e32 v95, v0
	v_mov_b32_e32 v112, v0
	v_mov_b32_e32 v113, v0
	v_mov_b32_e32 v114, v0
	v_mov_b32_e32 v115, v0
	v_mov_b32_e32 v116, v0
	v_mov_b32_e32 v117, v0
	v_mov_b32_e32 v118, v0
	v_mov_b32_e32 v119, v0
	v_mov_b32_e32 v120, v0
	v_mov_b32_e32 v121, v0
	v_mov_b32_e32 v122, v0
	v_mov_b32_e32 v123, v0
	v_mov_b32_e32 v124, v0
	v_mov_b32_e32 v125, v0
	v_mov_b32_e32 v126, v0
	v_mov_b32_e32 v127, v0
	s_branch .LBB0_426

; #define PG8_STAGE(bufoff, gbase, voff) do { _Pragma("unroll") for (int _i = 0; _i < 2; ++_i) \
;         __builtin_amdgcn_global_load_lds((const unsigned*)((const char*)(gbase) + (voff)[_i]), (PG8_LAS unsigned*)(lds + (bufoff) + ldsw + _i * 8192), 16, 0, 0); } while (0)
; #define PG8_STAGE_NT(bufoff, gbase, voff) do { _Pragma("unroll") for (int _i = 0; _i < 2; ++_i) \
;         __builtin_amdgcn_global_load_lds((const unsigned*)((const char*)(gbase) + (voff)[_i]), (PG8_LAS unsigned*)(lds + (bufoff) + ldsw + _i * 8192), 16, 0, PG8_B_AUX); } while (0)
; #define PG8_LDA(dst, b, h) do { _Pragma("unroll") for (int m = 0; m < 4; ++m) _Pragma("unroll") for (int k = 0; k < 2; ++k) dst[m][k] = *(const PG8_LAS bf16x8*)(lds + PG8_SA(b, h) + aoff + m * 2048 + k * 1024); } while (0)
; #define PG8_LDB(dst, b, h) do { _Pragma("unroll") for (int n = 0; n < 2; ++n) _Pragma("unroll") for (int k = 0; k < 2; ++k) dst[n][k] = *(const PG8_LAS bf16x8*)(lds + PG8_SB(b, h) + boff + n * 2048 + k * 1024); } while (0)
; #define PG8_MMA(ai, bj, At, Bt) do { __builtin_amdgcn_s_setprio(1); _Pragma("unroll") for (int m = 0; m < 4; ++m) _Pragma("unroll") for (int n = 0; n < 2; ++n) _Pragma("unroll") for (int k = 0; k < 2; ++k) \
;         acc[ai][bj][m][n] = __builtin_amdgcn_mfma_f32_16x16x32_bf16(Bt[n][k], At[m][k], acc[ai][bj][m][n], 0, 0, 0); __builtin_amdgcn_s_setprio(0); } while (0)
; #define PG8_WAIT_V(n) asm volatile("s_waitcnt vmcnt(" #n ")" ::: "memory")
; #define PG8_WAIT_L(n) asm volatile("s_waitcnt lgkmcnt(" #n ")" ::: "memory")
; #define PG8_BAR __builtin_amdgcn_s_barrier()
; #define PG8_SCHED __builtin_amdgcn_sched_barrier(0)
; template <class Epi, class Sched, bool ALIGN_EPI = false, bool SP2 = false>
; __device__ __forceinline__ void gemm_phase(PG8_LAS unsigned char* lds, const Gemm g, const Sched& S, const Epi& E, int wid) {
;     ...
;             PG8_LDB(B0, 0, 0); PG8_LDB(B1, 0, 1); PG8_SCHED; PG8_LDA(At, 0, 0); PG8_STAGE(PG8_SA(1, 1), a1 + hstepA, voffA);
;             PG8_WAIT_V(8); PG8_WAIT_L(0); PG8_BAR; PG8_MMA(0, 0, At, B0); PG8_MMA(0, 1, At, B1); PG8_BAR; PG8_SCHED;
;             PG8_LDA(At, 0, 1); PG8_STAGE_NT(PG8_SB(0, 0), b2, voffB); PG8_STAGE_NT(PG8_SB(0, 1), b2 + hstepB, voffB); PG8_STAGE(PG8_SA(0, 0), a2, voffA);
;             PG8_WAIT_V(8); PG8_WAIT_L(0); PG8_BAR; PG8_MMA(1, 0, At, B0); PG8_MMA(1, 1, At, B1); PG8_BAR; PG8_SCHED;
.LBB0_426:
	ds_read_b128 v[144:147], v161
	ds_read_b128 v[148:151], v161 offset:1024
	ds_read_b128 v[152:155], v161 offset:2048
	ds_read_b128 v[166:169], v161 offset:3072
	ds_read_b128 v[170:173], v162
	ds_read_b128 v[174:177], v162 offset:1024
	ds_read_b128 v[178:181], v162 offset:2048
	ds_read_b128 v[182:185], v162 offset:3072
	s_add_u32 s4, s46, 0x100
	s_addc_u32 s5, s47, 0
	s_add_u32 s98, s46, 0x80
	s_addc_u32 s99, s47, 0
	s_add_u32 s100, s46, 0x104080
	s_addc_u32 s101, s47, 0
	s_cmp_eq_u32 s64, 60
	s_cselect_b32 s51, s43, s5
	s_cselect_b32 s50, s42, s4
	s_cselect_b32 s49, s45, s63
	s_cselect_b32 s48, s44, s62
	s_add_i32 m0, s23, 0xc000
	ds_read_b128 v[186:189], v163
	ds_read_b128 v[190:193], v163 offset:1024
	ds_read_b128 v[194:197], v163 offset:2048
	ds_read_b128 v[198:201], v163 offset:3072
	ds_read_b128 v[202:205], v163 offset:4096
	ds_read_b128 v[206:209], v163 offset:5120
	ds_read_b128 v[210:213], v163 offset:6144
	ds_read_b128 v[214:217], v163 offset:7168
	global_load_lds_dwordx4 v134, s[100:101]
	s_add_i32 m0, s23, 0xe000
	s_nop 0
	global_load_lds_dwordx4 v130, s[100:101]
	s_mov_b32 m0, s53
	s_nop 0
	global_load_lds_dwordx4 v134, s[98:99]
	s_mov_b32 m0, s54
	s_nop 0
	global_load_lds_dwordx4 v130, s[98:99]
	s_waitcnt vmcnt(8)
	s_waitcnt lgkmcnt(0)
	s_barrier
	s_waitcnt lgkmcnt(0)
	v_mfma_f32_16x16x32_bf16 v[124:127], v[144:147], v[186:189], v[124:127]
	v_mfma_f32_16x16x32_bf16 v[120:123], v[152:155], v[186:189], v[120:123]
	v_mfma_f32_16x16x32_bf16 v[116:119], v[144:147], v[194:197], v[116:119]
	v_mfma_f32_16x16x32_bf16 v[112:115], v[152:155], v[194:197], v[112:115]
	v_mfma_f32_16x16x32_bf16 v[92:95], v[144:147], v[202:205], v[92:95]
	v_mfma_f32_16x16x32_bf16 v[88:91], v[152:155], v[202:205], v[88:91]
	v_mfma_f32_16x16x32_bf16 v[76:79], v[144:147], v[210:213], v[76:79]
	v_mfma_f32_16x16x32_bf16 v[72:75], v[152:155], v[210:213], v[72:75]
	v_mfma_f32_16x16x32_bf16 v[124:127], v[148:151], v[190:193], v[124:127]
	v_mfma_f32_16x16x32_bf16 v[120:123], v[166:169], v[190:193], v[120:123]
	v_mfma_f32_16x16x32_bf16 v[116:119], v[148:151], v[198:201], v[116:119]
	v_mfma_f32_16x16x32_bf16 v[112:115], v[166:169], v[198:201], v[112:115]
	v_mfma_f32_16x16x32_bf16 v[92:95], v[148:151], v[206:209], v[92:95]
	v_mfma_f32_16x16x32_bf16 v[88:91], v[166:169], v[206:209], v[88:91]
	v_mfma_f32_16x16x32_bf16 v[76:79], v[148:151], v[214:217], v[76:79]
	v_mfma_f32_16x16x32_bf16 v[72:75], v[166:169], v[214:217], v[72:75]
	v_mfma_f32_16x16x32_bf16 v[108:111], v[170:173], v[186:189], v[108:111]
	v_mfma_f32_16x16x32_bf16 v[104:107], v[178:181], v[186:189], v[104:107]
	v_mfma_f32_16x16x32_bf16 v[100:103], v[170:173], v[194:197], v[100:103]
	v_mfma_f32_16x16x32_bf16 v[96:99], v[178:181], v[194:197], v[96:99]
	v_mfma_f32_16x16x32_bf16 v[84:87], v[170:173], v[202:205], v[84:87]
	v_mfma_f32_16x16x32_bf16 v[80:83], v[178:181], v[202:205], v[80:83]
	v_mfma_f32_16x16x32_bf16 v[68:71], v[170:173], v[210:213], v[68:71]
	v_mfma_f32_16x16x32_bf16 v[64:67], v[178:181], v[210:213], v[64:67]
	v_mfma_f32_16x16x32_bf16 v[108:111], v[174:177], v[190:193], v[108:111]
	v_mfma_f32_16x16x32_bf16 v[104:107], v[182:185], v[190:193], v[104:107]
	v_mfma_f32_16x16x32_bf16 v[100:103], v[174:177], v[198:201], v[100:103]
	v_mfma_f32_16x16x32_bf16 v[96:99], v[182:185], v[198:201], v[96:99]
	v_mfma_f32_16x16x32_bf16 v[84:87], v[174:177], v[206:209], v[84:87]
	v_mfma_f32_16x16x32_bf16 v[80:83], v[182:185], v[206:209], v[80:83]
	v_mfma_f32_16x16x32_bf16 v[68:71], v[174:177], v[214:217], v[68:71]
	v_mfma_f32_16x16x32_bf16 v[64:67], v[182:185], v[214:217], v[64:67]
	s_barrier
	s_add_i32 s46, s56, s17
	s_mov_b32 m0, s46
	ds_read_b128 v[186:189], v163 offset:16384
	ds_read_b128 v[190:193], v163 offset:17408
	ds_read_b128 v[194:197], v163 offset:18432
	ds_read_b128 v[198:201], v163 offset:19456
	ds_read_b128 v[202:205], v163 offset:20480
	ds_read_b128 v[206:209], v163 offset:21504
	ds_read_b128 v[210:213], v163 offset:22528
	ds_read_b128 v[214:217], v163 offset:23552
	global_load_lds_dwordx4 v132, s[48:49]
	s_add_i32 m0, s46, 0x2000
	s_add_u32 s46, s48, 0x104000
	s_addc_u32 s47, s49, 0
	s_add_i32 s65, s57, s17
	global_load_lds_dwordx4 v128, s[48:49]
	s_mov_b32 m0, s65
	s_nop 0
	global_load_lds_dwordx4 v132, s[46:47]
	s_add_i32 m0, s65, 0x2000
	s_nop 0
	global_load_lds_dwordx4 v128, s[46:47]
	s_waitcnt vmcnt(4)
	s_waitcnt lgkmcnt(0)
	s_barrier
	s_waitcnt lgkmcnt(0)
	v_mfma_f32_16x16x32_bf16 v[60:63], v[144:147], v[186:189], v[60:63]
	v_mfma_f32_16x16x32_bf16 v[56:59], v[152:155], v[186:189], v[56:59]
	v_mfma_f32_16x16x32_bf16 v[44:47], v[144:147], v[194:197], v[44:47]
	v_mfma_f32_16x16x32_bf16 v[40:43], v[152:155], v[194:197], v[40:43]
	v_mfma_f32_16x16x32_bf16 v[28:31], v[144:147], v[202:205], v[28:31]
	v_mfma_f32_16x16x32_bf16 v[24:27], v[152:155], v[202:205], v[24:27]
	v_mfma_f32_16x16x32_bf16 v[12:15], v[144:147], v[210:213], v[12:15]
	v_mfma_f32_16x16x32_bf16 v[8:11], v[152:155], v[210:213], v[8:11]
	v_mfma_f32_16x16x32_bf16 v[60:63], v[148:151], v[190:193], v[60:63]
	v_mfma_f32_16x16x32_bf16 v[56:59], v[166:169], v[190:193], v[56:59]
	v_mfma_f32_16x16x32_bf16 v[44:47], v[148:151], v[198:201], v[44:47]
	v_mfma_f32_16x16x32_bf16 v[40:43], v[166:169], v[198:201], v[40:43]
	v_mfma_f32_16x16x32_bf16 v[28:31], v[148:151], v[206:209], v[28:31]
	v_mfma_f32_16x16x32_bf16 v[24:27], v[166:169], v[206:209], v[24:27]
	v_mfma_f32_16x16x32_bf16 v[12:15], v[148:151], v[214:217], v[12:15]
	v_mfma_f32_16x16x32_bf16 v[8:11], v[166:169], v[214:217], v[8:11]
	v_mfma_f32_16x16x32_bf16 v[52:55], v[170:173], v[186:189], v[52:55]
	v_mfma_f32_16x16x32_bf16 v[48:51], v[178:181], v[186:189], v[48:51]
	v_mfma_f32_16x16x32_bf16 v[36:39], v[170:173], v[194:197], v[36:39]
	v_mfma_f32_16x16x32_bf16 v[32:35], v[178:181], v[194:197], v[32:35]
	v_mfma_f32_16x16x32_bf16 v[20:23], v[170:173], v[202:205], v[20:23]
	v_mfma_f32_16x16x32_bf16 v[16:19], v[178:181], v[202:205], v[16:19]
	v_mfma_f32_16x16x32_bf16 v[4:7], v[170:173], v[210:213], v[4:7]
	v_mfma_f32_16x16x32_bf16 v[0:3], v[178:181], v[210:213], v[0:3]
	v_mfma_f32_16x16x32_bf16 v[52:55], v[174:177], v[190:193], v[52:55]
	v_mfma_f32_16x16x32_bf16 v[48:51], v[182:185], v[190:193], v[48:51]
	v_mfma_f32_16x16x32_bf16 v[36:39], v[174:177], v[198:201], v[36:39]
	v_mfma_f32_16x16x32_bf16 v[32:35], v[182:185], v[198:201], v[32:35]
	v_mfma_f32_16x16x32_bf16 v[20:23], v[174:177], v[206:209], v[20:23]
	v_mfma_f32_16x16x32_bf16 v[16:19], v[182:185], v[206:209], v[16:19]
	v_mfma_f32_16x16x32_bf16 v[4:7], v[174:177], v[214:217], v[4:7]
	v_mfma_f32_16x16x32_bf16 v[0:3], v[182:185], v[214:217], v[0:3]
	s_barrier
; #define PG8_STAGE(bufoff, gbase, voff) do { _Pragma("unroll") for (int _i = 0; _i < 2; ++_i) \
;         __builtin_amdgcn_global_load_lds((const unsigned*)((const char*)(gbase) + (voff)[_i]), (PG8_LAS unsigned*)(lds + (bufoff) + ldsw + _i * 8192), 16, 0, 0); } while (0)
; #define PG8_STAGE_NT(bufoff, gbase, voff) do { _Pragma("unroll") for (int _i = 0; _i < 2; ++_i) \
;         __builtin_amdgcn_global_load_lds((const unsigned*)((const char*)(gbase) + (voff)[_i]), (PG8_LAS unsigned*)(lds + (bufoff) + ldsw + _i * 8192), 16, 0, PG8_B_AUX); } while (0)
; #define PG8_LDA(dst, b, h) do { _Pragma("unroll") for (int m = 0; m < 4; ++m) _Pragma("unroll") for (int k = 0; k < 2; ++k) dst[m][k] = *(const PG8_LAS bf16x8*)(lds + PG8_SA(b, h) + aoff + m * 2048 + k * 1024); } while (0)
; #define PG8_LDB(dst, b, h) do { _Pragma("unroll") for (int n = 0; n < 2; ++n) _Pragma("unroll") for (int k = 0; k < 2; ++k) dst[n][k] = *(const PG8_LAS bf16x8*)(lds + PG8_SB(b, h) + boff + n * 2048 + k * 1024); } while (0)
; #define PG8_MMA(ai, bj, At, Bt) do { __builtin_amdgcn_s_setprio(1); _Pragma("unroll") for (int m = 0; m < 4; ++m) _Pragma("unroll") for (int n = 0; n < 2; ++n) _Pragma("unroll") for (int k = 0; k < 2; ++k) \
;         acc[ai][bj][m][n] = __builtin_amdgcn_mfma_f32_16x16x32_bf16(Bt[n][k], At[m][k], acc[ai][bj][m][n], 0, 0, 0); __builtin_amdgcn_s_setprio(0); } while (0)
; #define PG8_WAIT_V(n) asm volatile("s_waitcnt vmcnt(" #n ")" ::: "memory")
; #define PG8_WAIT_L(n) asm volatile("s_waitcnt lgkmcnt(" #n ")" ::: "memory")
; #define PG8_BAR __builtin_amdgcn_s_barrier()
; #define PG8_SCHED __builtin_amdgcn_sched_barrier(0)
; template <class Epi, class Sched, bool ALIGN_EPI = false, bool SP2 = false>
; __device__ __forceinline__ void gemm_phase(PG8_LAS unsigned char* lds, const Gemm g, const Sched& S, const Epi& E, int wid) {
;     ...
;             PG8_LDB(B0, 1, 0); PG8_LDB(B1, 1, 1); PG8_SCHED; PG8_LDA(At, 1, 0); PG8_STAGE(PG8_SA(0, 1), a2 + hstepA, voffA);
;             PG8_WAIT_V(8); PG8_WAIT_L(0); PG8_BAR; PG8_MMA(0, 0, At, B0); PG8_MMA(0, 1, At, B1); PG8_BAR; PG8_SCHED;
;             PG8_LDA(At, 1, 1); PG8_STAGE_NT(PG8_SB(1, 0), b3, voffB); PG8_STAGE_NT(PG8_SB(1, 1), b3 + hstepB, voffB); PG8_STAGE(PG8_SA(1, 0), a3, voffA);
;             PG8_WAIT_V(8); PG8_WAIT_L(0); PG8_BAR; PG8_MMA(1, 0, At, B0); PG8_MMA(1, 1, At, B1); PG8_BAR; PG8_SCHED;
	s_add_i32 s65, 0, 0x18000
	v_add_u32_e32 v165, s65, v159
	s_add_i32 s66, 0, 0x1c000
	ds_read_b128 v[144:147], v165
	ds_read_b128 v[148:151], v165 offset:1024
	ds_read_b128 v[152:155], v165 offset:2048
	ds_read_b128 v[166:169], v165 offset:3072
	v_add_u32_e32 v165, s66, v159
	ds_read_b128 v[170:173], v165
	ds_read_b128 v[174:177], v165 offset:1024
	ds_read_b128 v[178:181], v165 offset:2048
	ds_read_b128 v[182:185], v165 offset:3072
	s_add_u32 s46, s50, 0x104000
	s_addc_u32 s47, s51, 0
	s_mov_b32 m0, s25
	ds_read_b128 v[186:189], v163 offset:32768
	ds_read_b128 v[190:193], v163 offset:33792
	ds_read_b128 v[194:197], v163 offset:34816
	ds_read_b128 v[198:201], v163 offset:35840
	ds_read_b128 v[202:205], v163 offset:36864
	ds_read_b128 v[206:209], v163 offset:37888
	ds_read_b128 v[210:213], v163 offset:38912
	ds_read_b128 v[214:217], v163 offset:39936
	global_load_lds_dwordx4 v134, s[46:47]
	s_mov_b32 m0, s29
	s_nop 0
	global_load_lds_dwordx4 v130, s[46:47]
	s_mov_b32 m0, s23
	s_nop 0
	global_load_lds_dwordx4 v134, s[50:51]
	s_mov_b32 m0, s24
	s_nop 0
	global_load_lds_dwordx4 v130, s[50:51]
	s_waitcnt vmcnt(8)
	s_waitcnt lgkmcnt(0)
	s_barrier
	s_waitcnt lgkmcnt(0)
	v_mfma_f32_16x16x32_bf16 v[124:127], v[144:147], v[186:189], v[124:127]
	v_mfma_f32_16x16x32_bf16 v[120:123], v[152:155], v[186:189], v[120:123]
	v_mfma_f32_16x16x32_bf16 v[116:119], v[144:147], v[194:197], v[116:119]
	v_mfma_f32_16x16x32_bf16 v[112:115], v[152:155], v[194:197], v[112:115]
	v_mfma_f32_16x16x32_bf16 v[92:95], v[144:147], v[202:205], v[92:95]
	v_mfma_f32_16x16x32_bf16 v[88:91], v[152:155], v[202:205], v[88:91]
	v_mfma_f32_16x16x32_bf16 v[76:79], v[144:147], v[210:213], v[76:79]
	v_mfma_f32_16x16x32_bf16 v[72:75], v[152:155], v[210:213], v[72:75]
	v_mfma_f32_16x16x32_bf16 v[124:127], v[148:151], v[190:193], v[124:127]
	v_mfma_f32_16x16x32_bf16 v[120:123], v[166:169], v[190:193], v[120:123]
	v_mfma_f32_16x16x32_bf16 v[116:119], v[148:151], v[198:201], v[116:119]
	v_mfma_f32_16x16x32_bf16 v[112:115], v[166:169], v[198:201], v[112:115]
	v_mfma_f32_16x16x32_bf16 v[92:95], v[148:151], v[206:209], v[92:95]
	v_mfma_f32_16x16x32_bf16 v[88:91], v[166:169], v[206:209], v[88:91]
	v_mfma_f32_16x16x32_bf16 v[76:79], v[148:151], v[214:217], v[76:79]
	v_mfma_f32_16x16x32_bf16 v[72:75], v[166:169], v[214:217], v[72:75]
	v_mfma_f32_16x16x32_bf16 v[108:111], v[170:173], v[186:189], v[108:111]
	v_mfma_f32_16x16x32_bf16 v[104:107], v[178:181], v[186:189], v[104:107]
	v_mfma_f32_16x16x32_bf16 v[100:103], v[170:173], v[194:197], v[100:103]
	v_mfma_f32_16x16x32_bf16 v[96:99], v[178:181], v[194:197], v[96:99]
	v_mfma_f32_16x16x32_bf16 v[84:87], v[170:173], v[202:205], v[84:87]
	v_mfma_f32_16x16x32_bf16 v[80:83], v[178:181], v[202:205], v[80:83]
	v_mfma_f32_16x16x32_bf16 v[68:71], v[170:173], v[210:213], v[68:71]
	v_mfma_f32_16x16x32_bf16 v[64:67], v[178:181], v[210:213], v[64:67]
	v_mfma_f32_16x16x32_bf16 v[108:111], v[174:177], v[190:193], v[108:111]
	v_mfma_f32_16x16x32_bf16 v[104:107], v[182:185], v[190:193], v[104:107]
	v_mfma_f32_16x16x32_bf16 v[100:103], v[174:177], v[198:201], v[100:103]
	v_mfma_f32_16x16x32_bf16 v[96:99], v[182:185], v[198:201], v[96:99]
	v_mfma_f32_16x16x32_bf16 v[84:87], v[174:177], v[206:209], v[84:87]
	v_mfma_f32_16x16x32_bf16 v[80:83], v[182:185], v[206:209], v[80:83]
	v_mfma_f32_16x16x32_bf16 v[68:71], v[174:177], v[214:217], v[68:71]
	v_mfma_f32_16x16x32_bf16 v[64:67], v[182:185], v[214:217], v[64:67]
	s_barrier
	s_add_i32 s46, s65, s17
	s_mov_b32 m0, s46
	s_add_u32 s98, s48, 0x80
	s_addc_u32 s99, s49, 0
	ds_read_b128 v[186:189], v163 offset:49152
	ds_read_b128 v[190:193], v163 offset:50176
	ds_read_b128 v[194:197], v163 offset:51200
	ds_read_b128 v[198:201], v163 offset:52224
	ds_read_b128 v[202:205], v163 offset:53248
	ds_read_b128 v[206:209], v163 offset:54272
	ds_read_b128 v[210:213], v163 offset:55296
	ds_read_b128 v[214:217], v163 offset:56320
	global_load_lds_dwordx4 v132, s[98:99]
	s_add_i32 m0, s46, 0x2000
	s_add_u32 s46, s48, 0x104080
	s_addc_u32 s47, s49, 0
	s_add_i32 s48, s66, s17
	global_load_lds_dwordx4 v128, s[98:99]
	s_mov_b32 m0, s48
	s_nop 0
	global_load_lds_dwordx4 v132, s[46:47]
	s_add_i32 m0, s48, 0x2000
	s_nop 0
	global_load_lds_dwordx4 v128, s[46:47]
	s_waitcnt vmcnt(4)
	s_waitcnt lgkmcnt(0)
	s_barrier
	s_waitcnt lgkmcnt(0)
	v_mfma_f32_16x16x32_bf16 v[60:63], v[144:147], v[186:189], v[60:63]
	v_mfma_f32_16x16x32_bf16 v[56:59], v[152:155], v[186:189], v[56:59]
	v_mfma_f32_16x16x32_bf16 v[44:47], v[144:147], v[194:197], v[44:47]
	v_mfma_f32_16x16x32_bf16 v[40:43], v[152:155], v[194:197], v[40:43]
	v_mfma_f32_16x16x32_bf16 v[28:31], v[144:147], v[202:205], v[28:31]
	v_mfma_f32_16x16x32_bf16 v[24:27], v[152:155], v[202:205], v[24:27]
	v_mfma_f32_16x16x32_bf16 v[12:15], v[144:147], v[210:213], v[12:15]
	v_mfma_f32_16x16x32_bf16 v[8:11], v[152:155], v[210:213], v[8:11]
	v_mfma_f32_16x16x32_bf16 v[60:63], v[148:151], v[190:193], v[60:63]
	v_mfma_f32_16x16x32_bf16 v[56:59], v[166:169], v[190:193], v[56:59]
	v_mfma_f32_16x16x32_bf16 v[44:47], v[148:151], v[198:201], v[44:47]
	v_mfma_f32_16x16x32_bf16 v[40:43], v[166:169], v[198:201], v[40:43]
	v_mfma_f32_16x16x32_bf16 v[28:31], v[148:151], v[206:209], v[28:31]
	v_mfma_f32_16x16x32_bf16 v[24:27], v[166:169], v[206:209], v[24:27]
	v_mfma_f32_16x16x32_bf16 v[12:15], v[148:151], v[214:217], v[12:15]
	v_mfma_f32_16x16x32_bf16 v[8:11], v[166:169], v[214:217], v[8:11]
	v_mfma_f32_16x16x32_bf16 v[52:55], v[170:173], v[186:189], v[52:55]
	v_mfma_f32_16x16x32_bf16 v[48:51], v[178:181], v[186:189], v[48:51]
	v_mfma_f32_16x16x32_bf16 v[36:39], v[170:173], v[194:197], v[36:39]
	v_mfma_f32_16x16x32_bf16 v[32:35], v[178:181], v[194:197], v[32:35]
	v_mfma_f32_16x16x32_bf16 v[20:23], v[170:173], v[202:205], v[20:23]
	v_mfma_f32_16x16x32_bf16 v[16:19], v[178:181], v[202:205], v[16:19]
	v_mfma_f32_16x16x32_bf16 v[4:7], v[170:173], v[210:213], v[4:7]
	v_mfma_f32_16x16x32_bf16 v[0:3], v[178:181], v[210:213], v[0:3]
	v_mfma_f32_16x16x32_bf16 v[52:55], v[174:177], v[190:193], v[52:55]
	v_mfma_f32_16x16x32_bf16 v[48:51], v[182:185], v[190:193], v[48:51]
	v_mfma_f32_16x16x32_bf16 v[36:39], v[174:177], v[198:201], v[36:39]
	v_mfma_f32_16x16x32_bf16 v[32:35], v[182:185], v[198:201], v[32:35]
	v_mfma_f32_16x16x32_bf16 v[20:23], v[174:177], v[206:209], v[20:23]
	v_mfma_f32_16x16x32_bf16 v[16:19], v[182:185], v[206:209], v[16:19]
	v_mfma_f32_16x16x32_bf16 v[4:7], v[174:177], v[214:217], v[4:7]
	v_mfma_f32_16x16x32_bf16 v[0:3], v[182:185], v[214:217], v[0:3]
	s_add_i32 s64, s64, 2
	s_add_u32 s62, s62, 0x100
	s_addc_u32 s63, s63, 0
	s_cmp_gt_u32 s64, 61
	s_mov_b64 s[46:47], s[4:5]
	s_cbranch_scc0 .Lrot_head_2
	s_barrier
	s_and_b64 vcc, exec, s[40:41]
	s_cbranch_vccz .LBB0_429
	s_barrier

; template <class Epi, class Sched, bool ALIGN_EPI = false, bool SP2 = false>
; __device__ __forceinline__ void gemm_phase(PG8_LAS unsigned char* lds, const Gemm g, const Sched& S, const Epi& E, int wid) {
;     ...
; #pragma unroll
;         for (int a = 0; a < 2; ++a)
; #pragma unroll
;             for (int b = 0; b < 2; ++b)
; #pragma unroll
;                 for (int m = 0; m < 4; ++m)
; #pragma unroll
;                     for (int n = 0; n < 2; ++n) acc[a][b][m][n] = (f32x4){0.f, 0.f, 0.f, 0.f};
.LBB0_1036:
	s_add_u32 s65, s52, 0x100
	v_mov_b32_e32 v0, 0
	s_addc_u32 s66, s53, 0
	s_mov_b32 s67, -2
	s_waitcnt lgkmcnt(0)
	v_mov_b32_e32 v1, v0
	v_mov_b32_e32 v2, v0
	v_mov_b32_e32 v3, v0
	v_mov_b32_e32 v4, v0
	v_mov_b32_e32 v5, v0
	v_mov_b32_e32 v6, v0
	v_mov_b32_e32 v7, v0
	v_mov_b32_e32 v16, v0
	v_mov_b32_e32 v17, v0
	v_mov_b32_e32 v18, v0
	v_mov_b32_e32 v19, v0
	s_waitcnt vmcnt(0)
	v_mov_b32_e32 v20, v0
	v_mov_b32_e32 v21, v0
	v_mov_b32_e32 v22, v0
	v_mov_b32_e32 v23, v0
	v_mov_b32_e32 v32, v0
	v_mov_b32_e32 v33, v0
	v_mov_b32_e32 v34, v0
	v_mov_b32_e32 v35, v0
	v_mov_b32_e32 v36, v0
	v_mov_b32_e32 v37, v0
	v_mov_b32_e32 v38, v0
	v_mov_b32_e32 v39, v0
	v_mov_b32_e32 v48, v0
	v_mov_b32_e32 v49, v0
	v_mov_b32_e32 v50, v0
	v_mov_b32_e32 v51, v0
	v_mov_b32_e32 v52, v0
	v_mov_b32_e32 v53, v0
	v_mov_b32_e32 v54, v0
	v_mov_b32_e32 v55, v0
	v_mov_b32_e32 v8, v0
	v_mov_b32_e32 v9, v0
	v_mov_b32_e32 v10, v0
	v_mov_b32_e32 v11, v0
	v_mov_b32_e32 v12, v0
	v_mov_b32_e32 v13, v0
	v_mov_b32_e32 v14, v0
	v_mov_b32_e32 v15, v0
	v_mov_b32_e32 v24, v0
	v_mov_b32_e32 v25, v0
	v_mov_b32_e32 v26, v0
	v_mov_b32_e32 v27, v0
	v_mov_b32_e32 v28, v0
	v_mov_b32_e32 v29, v0
	v_mov_b32_e32 v30, v0
	v_mov_b32_e32 v31, v0
	v_mov_b32_e32 v40, v0
	v_mov_b32_e32 v41, v0
	v_mov_b32_e32 v42, v0
	v_mov_b32_e32 v43, v0
	v_mov_b32_e32 v44, v0
	v_mov_b32_e32 v45, v0
	v_mov_b32_e32 v46, v0
	v_mov_b32_e32 v47, v0
	v_mov_b32_e32 v56, v0
	v_mov_b32_e32 v57, v0
	v_mov_b32_e32 v58, v0
	v_mov_b32_e32 v59, v0
	v_mov_b32_e32 v60, v0
	v_mov_b32_e32 v61, v0
	v_mov_b32_e32 v62, v0
	v_mov_b32_e32 v63, v0
	v_mov_b32_e32 v64, v0
	v_mov_b32_e32 v65, v0
	v_mov_b32_e32 v66, v0
	v_mov_b32_e32 v67, v0
	v_mov_b32_e32 v68, v0
	v_mov_b32_e32 v69, v0
	v_mov_b32_e32 v70, v0
	v_mov_b32_e32 v71, v0
	v_mov_b32_e32 v80, v0
	v_mov_b32_e32 v81, v0
	v_mov_b32_e32 v82, v0
	v_mov_b32_e32 v83, v0
	v_mov_b32_e32 v84, v0
	v_mov_b32_e32 v85, v0
	v_mov_b32_e32 v86, v0
	v_mov_b32_e32 v87, v0
	v_mov_b32_e32 v96, v0
	v_mov_b32_e32 v97, v0
	v_mov_b32_e32 v98, v0
	v_mov_b32_e32 v99, v0
	v_mov_b32_e32 v100, v0
	v_mov_b32_e32 v101, v0
	v_mov_b32_e32 v102, v0
	v_mov_b32_e32 v103, v0
	v_mov_b32_e32 v120, v0
	v_mov_b32_e32 v121, v0
	v_mov_b32_e32 v122, v0
	v_mov_b32_e32 v123, v0
	v_mov_b32_e32 v124, v0
	v_mov_b32_e32 v125, v0
	v_mov_b32_e32 v126, v0
	v_mov_b32_e32 v127, v0
	v_mov_b32_e32 v72, v0
	v_mov_b32_e32 v73, v0
	v_mov_b32_e32 v74, v0
	v_mov_b32_e32 v75, v0
	v_mov_b32_e32 v76, v0
	v_mov_b32_e32 v77, v0
	v_mov_b32_e32 v78, v0
	v_mov_b32_e32 v79, v0
	v_mov_b32_e32 v88, v0
	v_mov_b32_e32 v89, v0
	v_mov_b32_e32 v90, v0
	v_mov_b32_e32 v91, v0
	v_mov_b32_e32 v92, v0
	v_mov_b32_e32 v93, v0
	v_mov_b32_e32 v94, v0
	v_mov_b32_e32 v95, v0
	v_mov_b32_e32 v108, v0
	v_mov_b32_e32 v109, v0
	v_mov_b32_e32 v110, v0
	v_mov_b32_e32 v111, v0
	v_mov_b32_e32 v112, v0
	v_mov_b32_e32 v113, v0
	v_mov_b32_e32 v114, v0
	v_mov_b32_e32 v115, v0
	v_mov_b32_e32 v132, v0
	v_mov_b32_e32 v133, v0
	v_mov_b32_e32 v134, v0
	v_mov_b32_e32 v135, v0
	v_mov_b32_e32 v136, v0
	v_mov_b32_e32 v137, v0
	v_mov_b32_e32 v138, v0
	v_mov_b32_e32 v139, v0
	s_branch .LBB0_1037

; #define PG8_STAGE(bufoff, gbase, voff) do { _Pragma("unroll") for (int _i = 0; _i < 2; ++_i) \
;         __builtin_amdgcn_global_load_lds((const unsigned*)((const char*)(gbase) + (voff)[_i]), (PG8_LAS unsigned*)(lds + (bufoff) + ldsw + _i * 8192), 16, 0, 0); } while (0)
; #define PG8_STAGE_NT(bufoff, gbase, voff) do { _Pragma("unroll") for (int _i = 0; _i < 2; ++_i) \
;         __builtin_amdgcn_global_load_lds((const unsigned*)((const char*)(gbase) + (voff)[_i]), (PG8_LAS unsigned*)(lds + (bufoff) + ldsw + _i * 8192), 16, 0, PG8_B_AUX); } while (0)
; #define PG8_LDA(dst, b, h) do { _Pragma("unroll") for (int m = 0; m < 4; ++m) _Pragma("unroll") for (int k = 0; k < 2; ++k) dst[m][k] = *(const PG8_LAS bf16x8*)(lds + PG8_SA(b, h) + aoff + m * 2048 + k * 1024); } while (0)
; #define PG8_LDB(dst, b, h) do { _Pragma("unroll") for (int n = 0; n < 2; ++n) _Pragma("unroll") for (int k = 0; k < 2; ++k) dst[n][k] = *(const PG8_LAS bf16x8*)(lds + PG8_SB(b, h) + boff + n * 2048 + k * 1024); } while (0)
; #define PG8_WAIT_V(n) asm volatile("s_waitcnt vmcnt(" #n ")" ::: "memory")
; #define PG8_WAIT_L(n) asm volatile("s_waitcnt lgkmcnt(" #n ")" ::: "memory")
; #define PG8_BAR __builtin_amdgcn_s_barrier()
; template <class Epi, class Sched, bool ALIGN_EPI = false, bool SP2 = false>
; __device__ __forceinline__ void gemm_phase(PG8_LAS unsigned char* lds, const Gemm g, const Sched& S, const Epi& E, int wid) {
;     ...
;         for (int t = 0; t < nt; t += 2) {
;             const bool last = (t == nt - 2);
;             const char* a1 = cA + (size_t)(t + 1) * kstep;
;             const char* a2 = last ? nA : cA + (size_t)(t + 2) * kstep; const char* b2 = last ? nB : cB + (size_t)(t + 2) * kstep;
;             const char* a3 = a2 + kstep; const char* b3 = b2 + kstep;
;             if (last && has_next) S.a_ready(nxt);
;             if constexpr (SP2) {
;             PG8_LDB(B0, 0, 0); PG8_LDB(B1, 0, 1); PG8_SCHED; PG8_LDA(At, 0, 0); PG8_STAGE(PG8_SA(1, 1), a1 + hstepA, voffA);
;             PG8_WAIT_V(8); PG8_WAIT_L(0); PG8_BAR; PG8_MMA(0, 0, At, B0); PG8_MMA(0, 1, At, B1); PG8_BAR; PG8_SCHED;
;             PG8_LDA(At, 0, 1); PG8_STAGE_NT(PG8_SB(0, 0), b2, voffB); PG8_STAGE_NT(PG8_SB(0, 1), b2 + hstepB, voffB); PG8_STAGE(PG8_SA(0, 0), a2, voffA);
;             PG8_WAIT_V(8); PG8_WAIT_L(0); PG8_BAR; PG8_MMA(1, 0, At, B0); PG8_MMA(1, 1, At, B1); PG8_BAR; PG8_SCHED;
.LBB0_1037:
	ds_read_b128 v[104:107], v221
	ds_read_b128 v[116:119], v221 offset:1024
	ds_read_b128 v[128:131], v221 offset:2048
	ds_read_b128 v[140:143], v221 offset:3072
	ds_read_b128 v[144:147], v222
	ds_read_b128 v[148:151], v222 offset:1024
	ds_read_b128 v[152:155], v222 offset:2048
	ds_read_b128 v[156:159], v222 offset:3072
	s_add_u32 s52, s50, 0x100
	s_addc_u32 s53, s51, 0
	s_add_u32 s98, s50, 0x80
	s_addc_u32 s99, s51, 0
	s_add_u32 s100, s50, 0x104080
	s_addc_u32 s101, s51, 0
	s_cmp_eq_u32 s67, 60
	s_cselect_b32 s57, s7, s53
	s_cselect_b32 s56, s6, s52
	s_cselect_b32 s55, s49, s66
	s_cselect_b32 s54, s48, s65
	s_add_i32 m0, s17, 0xc000
	ds_read_b128 v[160:163], v223
	ds_read_b128 v[164:167], v223 offset:1024
	ds_read_b128 v[168:171], v223 offset:2048
	ds_read_b128 v[172:175], v223 offset:3072
	ds_read_b128 v[176:179], v223 offset:4096
	ds_read_b128 v[180:183], v223 offset:5120
	ds_read_b128 v[200:203], v223 offset:6144
	ds_read_b128 v[204:207], v223 offset:7168
	global_load_lds_dwordx4 v184, s[100:101]
	s_add_i32 m0, s17, 0xe000
	s_nop 0
	global_load_lds_dwordx4 v188, s[100:101]
	s_mov_b32 m0, s25
	s_nop 0
	global_load_lds_dwordx4 v184, s[98:99]
	s_mov_b32 m0, s29
	s_nop 0
	global_load_lds_dwordx4 v188, s[98:99]
	s_waitcnt vmcnt(8)
	s_waitcnt lgkmcnt(0)
	s_barrier
	s_waitcnt lgkmcnt(0)
	v_mfma_f32_16x16x32_bf16 v[136:139], v[104:107], v[160:163], v[136:139]
	v_mfma_f32_16x16x32_bf16 v[132:135], v[128:131], v[160:163], v[132:135]
	v_mfma_f32_16x16x32_bf16 v[112:115], v[104:107], v[168:171], v[112:115]
	v_mfma_f32_16x16x32_bf16 v[108:111], v[128:131], v[168:171], v[108:111]
	v_mfma_f32_16x16x32_bf16 v[92:95], v[104:107], v[176:179], v[92:95]
	v_mfma_f32_16x16x32_bf16 v[88:91], v[128:131], v[176:179], v[88:91]
	v_mfma_f32_16x16x32_bf16 v[76:79], v[104:107], v[200:203], v[76:79]
	v_mfma_f32_16x16x32_bf16 v[72:75], v[128:131], v[200:203], v[72:75]
	v_mfma_f32_16x16x32_bf16 v[136:139], v[116:119], v[164:167], v[136:139]
	v_mfma_f32_16x16x32_bf16 v[132:135], v[140:143], v[164:167], v[132:135]
	v_mfma_f32_16x16x32_bf16 v[112:115], v[116:119], v[172:175], v[112:115]
	v_mfma_f32_16x16x32_bf16 v[108:111], v[140:143], v[172:175], v[108:111]
	v_mfma_f32_16x16x32_bf16 v[92:95], v[116:119], v[180:183], v[92:95]
	v_mfma_f32_16x16x32_bf16 v[88:91], v[140:143], v[180:183], v[88:91]
	v_mfma_f32_16x16x32_bf16 v[76:79], v[116:119], v[204:207], v[76:79]
	v_mfma_f32_16x16x32_bf16 v[72:75], v[140:143], v[204:207], v[72:75]
	v_mfma_f32_16x16x32_bf16 v[124:127], v[144:147], v[160:163], v[124:127]
	v_mfma_f32_16x16x32_bf16 v[120:123], v[152:155], v[160:163], v[120:123]
	v_mfma_f32_16x16x32_bf16 v[100:103], v[144:147], v[168:171], v[100:103]
	v_mfma_f32_16x16x32_bf16 v[96:99], v[152:155], v[168:171], v[96:99]
	v_mfma_f32_16x16x32_bf16 v[84:87], v[144:147], v[176:179], v[84:87]
	v_mfma_f32_16x16x32_bf16 v[80:83], v[152:155], v[176:179], v[80:83]
	v_mfma_f32_16x16x32_bf16 v[68:71], v[144:147], v[200:203], v[68:71]
	v_mfma_f32_16x16x32_bf16 v[64:67], v[152:155], v[200:203], v[64:67]
	v_mfma_f32_16x16x32_bf16 v[124:127], v[148:151], v[164:167], v[124:127]
	v_mfma_f32_16x16x32_bf16 v[120:123], v[156:159], v[164:167], v[120:123]
	v_mfma_f32_16x16x32_bf16 v[100:103], v[148:151], v[172:175], v[100:103]
	v_mfma_f32_16x16x32_bf16 v[96:99], v[156:159], v[172:175], v[96:99]
	v_mfma_f32_16x16x32_bf16 v[84:87], v[148:151], v[180:183], v[84:87]
	v_mfma_f32_16x16x32_bf16 v[80:83], v[156:159], v[180:183], v[80:83]
	v_mfma_f32_16x16x32_bf16 v[68:71], v[148:151], v[204:207], v[68:71]
	v_mfma_f32_16x16x32_bf16 v[64:67], v[156:159], v[204:207], v[64:67]
	s_barrier
	s_add_i32 s50, s60, s9
	s_mov_b32 m0, s50
	ds_read_b128 v[160:163], v223 offset:16384
	ds_read_b128 v[164:167], v223 offset:17408
	ds_read_b128 v[168:171], v223 offset:18432
	ds_read_b128 v[172:175], v223 offset:19456
	ds_read_b128 v[176:179], v223 offset:20480
	ds_read_b128 v[180:183], v223 offset:21504
	ds_read_b128 v[200:203], v223 offset:22528
	ds_read_b128 v[204:207], v223 offset:23552
	global_load_lds_dwordx4 v186, s[54:55]
	s_add_i32 m0, s50, 0x2000
	s_add_u32 s50, s54, 0x104000
	s_addc_u32 s51, s55, 0
	s_add_i32 s68, s61, s9
	global_load_lds_dwordx4 v190, s[54:55]
	s_mov_b32 m0, s68
	s_nop 0
	global_load_lds_dwordx4 v186, s[50:51]
	s_add_i32 m0, s68, 0x2000
	s_nop 0
	global_load_lds_dwordx4 v190, s[50:51]
	s_waitcnt vmcnt(4)
	s_waitcnt lgkmcnt(0)
	s_barrier
	s_waitcnt lgkmcnt(0)
	v_mfma_f32_16x16x32_bf16 v[60:63], v[104:107], v[160:163], v[60:63]
	v_mfma_f32_16x16x32_bf16 v[56:59], v[128:131], v[160:163], v[56:59]
	v_mfma_f32_16x16x32_bf16 v[44:47], v[104:107], v[168:171], v[44:47]
	v_mfma_f32_16x16x32_bf16 v[40:43], v[128:131], v[168:171], v[40:43]
	v_mfma_f32_16x16x32_bf16 v[28:31], v[104:107], v[176:179], v[28:31]
	v_mfma_f32_16x16x32_bf16 v[24:27], v[128:131], v[176:179], v[24:27]
	v_mfma_f32_16x16x32_bf16 v[12:15], v[104:107], v[200:203], v[12:15]
	v_mfma_f32_16x16x32_bf16 v[8:11], v[128:131], v[200:203], v[8:11]
	v_mfma_f32_16x16x32_bf16 v[60:63], v[116:119], v[164:167], v[60:63]
	v_mfma_f32_16x16x32_bf16 v[56:59], v[140:143], v[164:167], v[56:59]
	v_mfma_f32_16x16x32_bf16 v[44:47], v[116:119], v[172:175], v[44:47]
	v_mfma_f32_16x16x32_bf16 v[40:43], v[140:143], v[172:175], v[40:43]
	v_mfma_f32_16x16x32_bf16 v[28:31], v[116:119], v[180:183], v[28:31]
	v_mfma_f32_16x16x32_bf16 v[24:27], v[140:143], v[180:183], v[24:27]
	v_mfma_f32_16x16x32_bf16 v[12:15], v[116:119], v[204:207], v[12:15]
	v_mfma_f32_16x16x32_bf16 v[8:11], v[140:143], v[204:207], v[8:11]
	v_mfma_f32_16x16x32_bf16 v[52:55], v[144:147], v[160:163], v[52:55]
	v_mfma_f32_16x16x32_bf16 v[48:51], v[152:155], v[160:163], v[48:51]
	v_mfma_f32_16x16x32_bf16 v[36:39], v[144:147], v[168:171], v[36:39]
	v_mfma_f32_16x16x32_bf16 v[32:35], v[152:155], v[168:171], v[32:35]
	v_mfma_f32_16x16x32_bf16 v[20:23], v[144:147], v[176:179], v[20:23]
	v_mfma_f32_16x16x32_bf16 v[16:19], v[152:155], v[176:179], v[16:19]
	v_mfma_f32_16x16x32_bf16 v[4:7], v[144:147], v[200:203], v[4:7]
	v_mfma_f32_16x16x32_bf16 v[0:3], v[152:155], v[200:203], v[0:3]
	v_mfma_f32_16x16x32_bf16 v[52:55], v[148:151], v[164:167], v[52:55]
	v_mfma_f32_16x16x32_bf16 v[48:51], v[156:159], v[164:167], v[48:51]
	v_mfma_f32_16x16x32_bf16 v[36:39], v[148:151], v[172:175], v[36:39]
	v_mfma_f32_16x16x32_bf16 v[32:35], v[156:159], v[172:175], v[32:35]
	v_mfma_f32_16x16x32_bf16 v[20:23], v[148:151], v[180:183], v[20:23]
	v_mfma_f32_16x16x32_bf16 v[16:19], v[156:159], v[180:183], v[16:19]
	v_mfma_f32_16x16x32_bf16 v[4:7], v[148:151], v[204:207], v[4:7]
	v_mfma_f32_16x16x32_bf16 v[0:3], v[156:159], v[204:207], v[0:3]
	s_barrier
; #define PG8_STAGE(bufoff, gbase, voff) do { _Pragma("unroll") for (int _i = 0; _i < 2; ++_i) \
;         __builtin_amdgcn_global_load_lds((const unsigned*)((const char*)(gbase) + (voff)[_i]), (PG8_LAS unsigned*)(lds + (bufoff) + ldsw + _i * 8192), 16, 0, 0); } while (0)
; #define PG8_STAGE_NT(bufoff, gbase, voff) do { _Pragma("unroll") for (int _i = 0; _i < 2; ++_i) \
;         __builtin_amdgcn_global_load_lds((const unsigned*)((const char*)(gbase) + (voff)[_i]), (PG8_LAS unsigned*)(lds + (bufoff) + ldsw + _i * 8192), 16, 0, PG8_B_AUX); } while (0)
; #define PG8_LDA(dst, b, h) do { _Pragma("unroll") for (int m = 0; m < 4; ++m) _Pragma("unroll") for (int k = 0; k < 2; ++k) dst[m][k] = *(const PG8_LAS bf16x8*)(lds + PG8_SA(b, h) + aoff + m * 2048 + k * 1024); } while (0)
; #define PG8_LDB(dst, b, h) do { _Pragma("unroll") for (int n = 0; n < 2; ++n) _Pragma("unroll") for (int k = 0; k < 2; ++k) dst[n][k] = *(const PG8_LAS bf16x8*)(lds + PG8_SB(b, h) + boff + n * 2048 + k * 1024); } while (0)
; #define PG8_WAIT_V(n) asm volatile("s_waitcnt vmcnt(" #n ")" ::: "memory")
; #define PG8_WAIT_L(n) asm volatile("s_waitcnt lgkmcnt(" #n ")" ::: "memory")
; #define PG8_BAR __builtin_amdgcn_s_barrier()
; #define PG8_SCHED __builtin_amdgcn_sched_barrier(0)
; template <class Epi, class Sched, bool ALIGN_EPI = false, bool SP2 = false>
; __device__ __forceinline__ void gemm_phase(PG8_LAS unsigned char* lds, const Gemm g, const Sched& S, const Epi& E, int wid) {
;     ...
;         for (int t = 0; t < nt; t += 2) {
;             const bool last = (t == nt - 2);
;             const char* a1 = cA + (size_t)(t + 1) * kstep;
;             const char* a2 = last ? nA : cA + (size_t)(t + 2) * kstep; const char* b2 = last ? nB : cB + (size_t)(t + 2) * kstep;
;             const char* a3 = a2 + kstep; const char* b3 = b2 + kstep;
;             if (last && has_next) S.a_ready(nxt);
;     ...
;             PG8_LDB(B0, 1, 0); PG8_LDB(B1, 1, 1); PG8_SCHED; PG8_LDA(At, 1, 0); PG8_STAGE(PG8_SA(0, 1), a2 + hstepA, voffA);
;             PG8_WAIT_V(8); PG8_WAIT_L(0); PG8_BAR; PG8_MMA(0, 0, At, B0); PG8_MMA(0, 1, At, B1); PG8_BAR; PG8_SCHED;
;             PG8_LDA(At, 1, 1); PG8_STAGE_NT(PG8_SB(1, 0), b3, voffB); PG8_STAGE_NT(PG8_SB(1, 1), b3 + hstepB, voffB); PG8_STAGE(PG8_SA(1, 0), a3, voffA);
;             PG8_WAIT_V(8); PG8_WAIT_L(0); PG8_BAR; PG8_MMA(1, 0, At, B0); PG8_MMA(1, 1, At, B1); PG8_BAR; PG8_SCHED;
	s_add_i32 s68, 0, 0x18000
	v_add_u32_e32 v140, s68, v219
	s_add_i32 s69, 0, 0x1c000
	ds_read_b128 v[104:107], v140
	ds_read_b128 v[116:119], v140 offset:1024
	ds_read_b128 v[128:131], v140 offset:2048
	ds_read_b128 v[140:143], v140 offset:3072
	v_add_u32_e32 v156, s69, v219
	ds_read_b128 v[144:147], v156
	ds_read_b128 v[148:151], v156 offset:1024
	ds_read_b128 v[152:155], v156 offset:2048
	ds_read_b128 v[156:159], v156 offset:3072
	s_add_u32 s50, s56, 0x104000
	s_addc_u32 s51, s57, 0
	s_mov_b32 m0, s22
	ds_read_b128 v[160:163], v223 offset:32768
	ds_read_b128 v[164:167], v223 offset:33792
	ds_read_b128 v[168:171], v223 offset:34816
	ds_read_b128 v[172:175], v223 offset:35840
	ds_read_b128 v[176:179], v223 offset:36864
	ds_read_b128 v[180:183], v223 offset:37888
	ds_read_b128 v[200:203], v223 offset:38912
	ds_read_b128 v[204:207], v223 offset:39936
	global_load_lds_dwordx4 v184, s[50:51]
	s_mov_b32 m0, s23
	s_nop 0
	global_load_lds_dwordx4 v188, s[50:51]
	s_mov_b32 m0, s17
	s_nop 0
	global_load_lds_dwordx4 v184, s[56:57]
	s_mov_b32 m0, s19
	s_nop 0
	global_load_lds_dwordx4 v188, s[56:57]
	s_waitcnt vmcnt(8)
	s_waitcnt lgkmcnt(0)
	s_barrier
	s_waitcnt lgkmcnt(0)
	v_mfma_f32_16x16x32_bf16 v[136:139], v[104:107], v[160:163], v[136:139]
	v_mfma_f32_16x16x32_bf16 v[132:135], v[128:131], v[160:163], v[132:135]
	v_mfma_f32_16x16x32_bf16 v[112:115], v[104:107], v[168:171], v[112:115]
	v_mfma_f32_16x16x32_bf16 v[108:111], v[128:131], v[168:171], v[108:111]
	v_mfma_f32_16x16x32_bf16 v[92:95], v[104:107], v[176:179], v[92:95]
	v_mfma_f32_16x16x32_bf16 v[88:91], v[128:131], v[176:179], v[88:91]
	v_mfma_f32_16x16x32_bf16 v[76:79], v[104:107], v[200:203], v[76:79]
	v_mfma_f32_16x16x32_bf16 v[72:75], v[128:131], v[200:203], v[72:75]
	v_mfma_f32_16x16x32_bf16 v[136:139], v[116:119], v[164:167], v[136:139]
	v_mfma_f32_16x16x32_bf16 v[132:135], v[140:143], v[164:167], v[132:135]
	v_mfma_f32_16x16x32_bf16 v[112:115], v[116:119], v[172:175], v[112:115]
	v_mfma_f32_16x16x32_bf16 v[108:111], v[140:143], v[172:175], v[108:111]
	v_mfma_f32_16x16x32_bf16 v[92:95], v[116:119], v[180:183], v[92:95]
	v_mfma_f32_16x16x32_bf16 v[88:91], v[140:143], v[180:183], v[88:91]
	v_mfma_f32_16x16x32_bf16 v[76:79], v[116:119], v[204:207], v[76:79]
	v_mfma_f32_16x16x32_bf16 v[72:75], v[140:143], v[204:207], v[72:75]
	v_mfma_f32_16x16x32_bf16 v[124:127], v[144:147], v[160:163], v[124:127]
	v_mfma_f32_16x16x32_bf16 v[120:123], v[152:155], v[160:163], v[120:123]
	v_mfma_f32_16x16x32_bf16 v[100:103], v[144:147], v[168:171], v[100:103]
	v_mfma_f32_16x16x32_bf16 v[96:99], v[152:155], v[168:171], v[96:99]
	v_mfma_f32_16x16x32_bf16 v[84:87], v[144:147], v[176:179], v[84:87]
	v_mfma_f32_16x16x32_bf16 v[80:83], v[152:155], v[176:179], v[80:83]
	v_mfma_f32_16x16x32_bf16 v[68:71], v[144:147], v[200:203], v[68:71]
	v_mfma_f32_16x16x32_bf16 v[64:67], v[152:155], v[200:203], v[64:67]
	v_mfma_f32_16x16x32_bf16 v[124:127], v[148:151], v[164:167], v[124:127]
	v_mfma_f32_16x16x32_bf16 v[120:123], v[156:159], v[164:167], v[120:123]
	v_mfma_f32_16x16x32_bf16 v[100:103], v[148:151], v[172:175], v[100:103]
	v_mfma_f32_16x16x32_bf16 v[96:99], v[156:159], v[172:175], v[96:99]
	v_mfma_f32_16x16x32_bf16 v[84:87], v[148:151], v[180:183], v[84:87]
	v_mfma_f32_16x16x32_bf16 v[80:83], v[156:159], v[180:183], v[80:83]
	v_mfma_f32_16x16x32_bf16 v[68:71], v[148:151], v[204:207], v[68:71]
	v_mfma_f32_16x16x32_bf16 v[64:67], v[156:159], v[204:207], v[64:67]
	s_barrier
	s_add_i32 s50, s68, s9
	s_mov_b32 m0, s50
	s_add_u32 s98, s54, 0x80
	s_addc_u32 s99, s55, 0
	ds_read_b128 v[160:163], v223 offset:49152
	ds_read_b128 v[164:167], v223 offset:50176
	ds_read_b128 v[168:171], v223 offset:51200
	ds_read_b128 v[172:175], v223 offset:52224
	ds_read_b128 v[176:179], v223 offset:53248
	ds_read_b128 v[180:183], v223 offset:54272
	ds_read_b128 v[200:203], v223 offset:55296
	ds_read_b128 v[204:207], v223 offset:56320
	global_load_lds_dwordx4 v186, s[98:99]
	s_add_i32 m0, s50, 0x2000
	s_add_u32 s50, s54, 0x104080
	s_addc_u32 s51, s55, 0
	s_add_i32 s54, s69, s9
	global_load_lds_dwordx4 v190, s[98:99]
	s_mov_b32 m0, s54
	s_nop 0
	global_load_lds_dwordx4 v186, s[50:51]
	s_add_i32 m0, s54, 0x2000
	s_nop 0
	global_load_lds_dwordx4 v190, s[50:51]
	s_waitcnt vmcnt(4)
	s_waitcnt lgkmcnt(0)
	s_barrier
	s_waitcnt lgkmcnt(0)
	v_mfma_f32_16x16x32_bf16 v[60:63], v[104:107], v[160:163], v[60:63]
	v_mfma_f32_16x16x32_bf16 v[56:59], v[128:131], v[160:163], v[56:59]
	v_mfma_f32_16x16x32_bf16 v[44:47], v[104:107], v[168:171], v[44:47]
	v_mfma_f32_16x16x32_bf16 v[40:43], v[128:131], v[168:171], v[40:43]
	v_mfma_f32_16x16x32_bf16 v[28:31], v[104:107], v[176:179], v[28:31]
	v_mfma_f32_16x16x32_bf16 v[24:27], v[128:131], v[176:179], v[24:27]
	v_mfma_f32_16x16x32_bf16 v[12:15], v[104:107], v[200:203], v[12:15]
	v_mfma_f32_16x16x32_bf16 v[8:11], v[128:131], v[200:203], v[8:11]
	v_mfma_f32_16x16x32_bf16 v[60:63], v[116:119], v[164:167], v[60:63]
	v_mfma_f32_16x16x32_bf16 v[56:59], v[140:143], v[164:167], v[56:59]
	v_mfma_f32_16x16x32_bf16 v[44:47], v[116:119], v[172:175], v[44:47]
	v_mfma_f32_16x16x32_bf16 v[40:43], v[140:143], v[172:175], v[40:43]
	v_mfma_f32_16x16x32_bf16 v[28:31], v[116:119], v[180:183], v[28:31]
	v_mfma_f32_16x16x32_bf16 v[24:27], v[140:143], v[180:183], v[24:27]
	v_mfma_f32_16x16x32_bf16 v[12:15], v[116:119], v[204:207], v[12:15]
	v_mfma_f32_16x16x32_bf16 v[8:11], v[140:143], v[204:207], v[8:11]
	v_mfma_f32_16x16x32_bf16 v[52:55], v[144:147], v[160:163], v[52:55]
	v_mfma_f32_16x16x32_bf16 v[48:51], v[152:155], v[160:163], v[48:51]
	v_mfma_f32_16x16x32_bf16 v[36:39], v[144:147], v[168:171], v[36:39]
	v_mfma_f32_16x16x32_bf16 v[32:35], v[152:155], v[168:171], v[32:35]
	v_mfma_f32_16x16x32_bf16 v[20:23], v[144:147], v[176:179], v[20:23]
	v_mfma_f32_16x16x32_bf16 v[16:19], v[152:155], v[176:179], v[16:19]
	v_mfma_f32_16x16x32_bf16 v[4:7], v[144:147], v[200:203], v[4:7]
	v_mfma_f32_16x16x32_bf16 v[0:3], v[152:155], v[200:203], v[0:3]
	v_mfma_f32_16x16x32_bf16 v[52:55], v[148:151], v[164:167], v[52:55]
	v_mfma_f32_16x16x32_bf16 v[48:51], v[156:159], v[164:167], v[48:51]
	v_mfma_f32_16x16x32_bf16 v[36:39], v[148:151], v[172:175], v[36:39]
	v_mfma_f32_16x16x32_bf16 v[32:35], v[156:159], v[172:175], v[32:35]
	v_mfma_f32_16x16x32_bf16 v[20:23], v[148:151], v[180:183], v[20:23]
	v_mfma_f32_16x16x32_bf16 v[16:19], v[156:159], v[180:183], v[16:19]
	v_mfma_f32_16x16x32_bf16 v[4:7], v[148:151], v[204:207], v[4:7]
	v_mfma_f32_16x16x32_bf16 v[0:3], v[156:159], v[204:207], v[0:3]
	s_add_i32 s67, s67, 2
	s_add_u32 s65, s65, 0x100
	s_addc_u32 s66, s66, 0
	s_cmp_gt_u32 s67, 61
	s_mov_b64 s[50:51], s[52:53]
	s_cbranch_scc0 .Lrot_head_3
	s_barrier
	s_and_b64 vcc, exec, s[46:47]
	s_cbranch_vccz .LBB0_1040
	s_barrier

; template <class Epi, class Sched, bool ALIGN_EPI = false, bool SP2 = false>
; __device__ __forceinline__ void gemm_phase(PG8_LAS unsigned char* lds, const Gemm g, const Sched& S, const Epi& E, int wid) {
;     ...
; #pragma unroll
;         for (int a = 0; a < 2; ++a)
; #pragma unroll
;             for (int b = 0; b < 2; ++b)
; #pragma unroll
;                 for (int m = 0; m < 4; ++m)
; #pragma unroll
;                     for (int n = 0; n < 2; ++n) acc[a][b][m][n] = (f32x4){0.f, 0.f, 0.f, 0.f};
;         cur = nxt; cA = nA; cB = nB; ++ui;
.LBB0_1132:
	s_add_u32 s61, s48, 0x100
	v_mov_b32_e32 v0, 0
	s_addc_u32 s62, s49, 0
	s_mov_b32 s63, -2
	v_mov_b32_e32 v1, v0
	v_mov_b32_e32 v2, v0
	v_mov_b32_e32 v3, v0
	v_mov_b32_e32 v8, v0
	v_mov_b32_e32 v9, v0
	v_mov_b32_e32 v10, v0
	v_mov_b32_e32 v11, v0
	v_mov_b32_e32 v16, v0
	v_mov_b32_e32 v17, v0
	v_mov_b32_e32 v18, v0
	v_mov_b32_e32 v19, v0
	v_mov_b32_e32 v24, v0
	v_mov_b32_e32 v25, v0
	v_mov_b32_e32 v26, v0
	v_mov_b32_e32 v27, v0
	v_mov_b32_e32 v32, v0
	v_mov_b32_e32 v33, v0
	v_mov_b32_e32 v34, v0
	v_mov_b32_e32 v35, v0
	v_mov_b32_e32 v40, v0
	v_mov_b32_e32 v41, v0
	v_mov_b32_e32 v42, v0
	v_mov_b32_e32 v43, v0
	v_mov_b32_e32 v48, v0
	v_mov_b32_e32 v49, v0
	v_mov_b32_e32 v50, v0
	v_mov_b32_e32 v51, v0
	v_mov_b32_e32 v56, v0
	v_mov_b32_e32 v57, v0
	v_mov_b32_e32 v58, v0
	v_mov_b32_e32 v59, v0
	v_mov_b32_e32 v4, v0
	v_mov_b32_e32 v5, v0
	v_mov_b32_e32 v6, v0
	v_mov_b32_e32 v7, v0
	v_mov_b32_e32 v12, v0
	v_mov_b32_e32 v13, v0
	v_mov_b32_e32 v14, v0
	v_mov_b32_e32 v15, v0
	v_mov_b32_e32 v20, v0
	v_mov_b32_e32 v21, v0
	v_mov_b32_e32 v22, v0
	v_mov_b32_e32 v23, v0
	v_mov_b32_e32 v28, v0
	v_mov_b32_e32 v29, v0
	v_mov_b32_e32 v30, v0
	v_mov_b32_e32 v31, v0
	v_mov_b32_e32 v36, v0
	v_mov_b32_e32 v37, v0
	v_mov_b32_e32 v38, v0
	v_mov_b32_e32 v39, v0
	v_mov_b32_e32 v44, v0
	v_mov_b32_e32 v45, v0
	v_mov_b32_e32 v46, v0
	v_mov_b32_e32 v47, v0
	v_mov_b32_e32 v52, v0
	v_mov_b32_e32 v53, v0
	v_mov_b32_e32 v54, v0
	v_mov_b32_e32 v55, v0
	v_mov_b32_e32 v60, v0
	v_mov_b32_e32 v61, v0
	v_mov_b32_e32 v62, v0
	v_mov_b32_e32 v63, v0
	v_mov_b32_e32 v64, v0
	v_mov_b32_e32 v65, v0
	v_mov_b32_e32 v66, v0
	v_mov_b32_e32 v67, v0
	v_mov_b32_e32 v72, v0
	v_mov_b32_e32 v73, v0
	v_mov_b32_e32 v74, v0
	v_mov_b32_e32 v75, v0
	v_mov_b32_e32 v80, v0
	v_mov_b32_e32 v81, v0
	v_mov_b32_e32 v82, v0
	v_mov_b32_e32 v83, v0
	v_mov_b32_e32 v88, v0
	v_mov_b32_e32 v89, v0
	v_mov_b32_e32 v90, v0
	v_mov_b32_e32 v91, v0
	v_mov_b32_e32 v96, v0
	v_mov_b32_e32 v97, v0
	v_mov_b32_e32 v98, v0
	v_mov_b32_e32 v99, v0
	v_mov_b32_e32 v116, v0
	v_mov_b32_e32 v117, v0
	v_mov_b32_e32 v118, v0
	v_mov_b32_e32 v119, v0
	v_mov_b32_e32 v120, v0
	v_mov_b32_e32 v121, v0
	v_mov_b32_e32 v122, v0
	v_mov_b32_e32 v123, v0
	v_mov_b32_e32 v124, v0
	v_mov_b32_e32 v125, v0
	v_mov_b32_e32 v126, v0
	v_mov_b32_e32 v127, v0
	v_mov_b32_e32 v68, v0
	v_mov_b32_e32 v69, v0
	v_mov_b32_e32 v70, v0
	v_mov_b32_e32 v71, v0
	v_mov_b32_e32 v76, v0
	v_mov_b32_e32 v77, v0
	v_mov_b32_e32 v78, v0
	v_mov_b32_e32 v79, v0
	v_mov_b32_e32 v84, v0
	v_mov_b32_e32 v85, v0
	v_mov_b32_e32 v86, v0
	v_mov_b32_e32 v87, v0
	v_mov_b32_e32 v92, v0
	v_mov_b32_e32 v93, v0
	v_mov_b32_e32 v94, v0
	v_mov_b32_e32 v95, v0
	v_mov_b32_e32 v100, v0
	v_mov_b32_e32 v101, v0
	v_mov_b32_e32 v102, v0
	v_mov_b32_e32 v103, v0
	v_mov_b32_e32 v104, v0
	v_mov_b32_e32 v105, v0
	v_mov_b32_e32 v106, v0
	v_mov_b32_e32 v107, v0
	v_mov_b32_e32 v108, v0
	v_mov_b32_e32 v109, v0
	v_mov_b32_e32 v110, v0
	v_mov_b32_e32 v111, v0
	v_mov_b32_e32 v112, v0
	v_mov_b32_e32 v113, v0
	v_mov_b32_e32 v114, v0
	v_mov_b32_e32 v115, v0
	s_branch .LBB0_1133

; #define PG8_STAGE(bufoff, gbase, voff) do { _Pragma("unroll") for (int _i = 0; _i < 2; ++_i) \
;         __builtin_amdgcn_global_load_lds((const unsigned*)((const char*)(gbase) + (voff)[_i]), (PG8_LAS unsigned*)(lds + (bufoff) + ldsw + _i * 8192), 16, 0, 0); } while (0)
; #define PG8_STAGE_NT(bufoff, gbase, voff) do { _Pragma("unroll") for (int _i = 0; _i < 2; ++_i) \
;         __builtin_amdgcn_global_load_lds((const unsigned*)((const char*)(gbase) + (voff)[_i]), (PG8_LAS unsigned*)(lds + (bufoff) + ldsw + _i * 8192), 16, 0, PG8_B_AUX); } while (0)
; #define PG8_LDA(dst, b, h) do { _Pragma("unroll") for (int m = 0; m < 4; ++m) _Pragma("unroll") for (int k = 0; k < 2; ++k) dst[m][k] = *(const PG8_LAS bf16x8*)(lds + PG8_SA(b, h) + aoff + m * 2048 + k * 1024); } while (0)
; #define PG8_LDB(dst, b, h) do { _Pragma("unroll") for (int n = 0; n < 2; ++n) _Pragma("unroll") for (int k = 0; k < 2; ++k) dst[n][k] = *(const PG8_LAS bf16x8*)(lds + PG8_SB(b, h) + boff + n * 2048 + k * 1024); } while (0)
; #define PG8_WAIT_V(n) asm volatile("s_waitcnt vmcnt(" #n ")" ::: "memory")
; #define PG8_WAIT_L(n) asm volatile("s_waitcnt lgkmcnt(" #n ")" ::: "memory")
; #define PG8_BAR __builtin_amdgcn_s_barrier()
; template <class Epi, class Sched, bool ALIGN_EPI = false, bool SP2 = false>
; __device__ __forceinline__ void gemm_phase(PG8_LAS unsigned char* lds, const Gemm g, const Sched& S, const Epi& E, int wid) {
;     ...
;         for (int t = 0; t < nt; t += 2) {
;             const bool last = (t == nt - 2);
;             const char* a1 = cA + (size_t)(t + 1) * kstep;
;             const char* a2 = last ? nA : cA + (size_t)(t + 2) * kstep; const char* b2 = last ? nB : cB + (size_t)(t + 2) * kstep;
;             const char* a3 = a2 + kstep; const char* b3 = b2 + kstep;
;             if (last && has_next) S.a_ready(nxt);
;             if constexpr (SP2) {
;             PG8_LDB(B0, 0, 0); PG8_LDB(B1, 0, 1); PG8_SCHED; PG8_LDA(At, 0, 0); PG8_STAGE(PG8_SA(1, 1), a1 + hstepA, voffA);
;             PG8_WAIT_V(8); PG8_WAIT_L(0); PG8_BAR; PG8_MMA(0, 0, At, B0); PG8_MMA(0, 1, At, B1); PG8_BAR; PG8_SCHED;
;             PG8_LDA(At, 0, 1); PG8_STAGE_NT(PG8_SB(0, 0), b2, voffB); PG8_STAGE_NT(PG8_SB(0, 1), b2 + hstepB, voffB); PG8_STAGE(PG8_SA(0, 0), a2, voffA);
;             PG8_WAIT_V(8); PG8_WAIT_L(0); PG8_BAR; PG8_MMA(1, 0, At, B0); PG8_MMA(1, 1, At, B1); PG8_BAR; PG8_SCHED;
.LBB0_1133:
	ds_read_b128 v[144:147], v155
	ds_read_b128 v[148:151], v155 offset:1024
	ds_read_b128 v[160:163], v155 offset:2048
	ds_read_b128 v[164:167], v155 offset:3072
	ds_read_b128 v[168:171], v156
	ds_read_b128 v[172:175], v156 offset:1024
	ds_read_b128 v[176:179], v156 offset:2048
	ds_read_b128 v[180:183], v156 offset:3072
	s_add_u32 s4, s46, 0x100
	s_addc_u32 s5, s47, 0
	s_add_u32 s98, s46, 0x80
	s_addc_u32 s99, s47, 0
	s_add_u32 s100, s46, 0x104080
	s_addc_u32 s101, s47, 0
	s_cmp_eq_u32 s63, 60
	s_cselect_b32 s51, s43, s5
	s_cselect_b32 s50, s42, s4
	s_cselect_b32 s49, s45, s62
	s_cselect_b32 s48, s44, s61
	s_add_i32 m0, s22, 0xc000
	ds_read_b128 v[184:187], v157
	ds_read_b128 v[188:191], v157 offset:1024
	ds_read_b128 v[192:195], v157 offset:2048
	ds_read_b128 v[196:199], v157 offset:3072
	ds_read_b128 v[200:203], v157 offset:4096
	ds_read_b128 v[204:207], v157 offset:5120
	ds_read_b128 v[208:211], v157 offset:6144
	ds_read_b128 v[212:215], v157 offset:7168
	global_load_lds_dwordx4 v134, s[100:101]
	s_add_i32 m0, s22, 0xe000
	s_nop 0
	global_load_lds_dwordx4 v130, s[100:101]
	s_mov_b32 m0, s52
	s_nop 0
	global_load_lds_dwordx4 v134, s[98:99]
	s_mov_b32 m0, s53
	s_nop 0
	global_load_lds_dwordx4 v130, s[98:99]
	s_waitcnt vmcnt(8)
	s_waitcnt lgkmcnt(0)
	s_barrier
	s_waitcnt lgkmcnt(0)
	v_mfma_f32_16x16x32_bf16 v[112:115], v[144:147], v[184:187], v[112:115]
	v_mfma_f32_16x16x32_bf16 v[108:111], v[160:163], v[184:187], v[108:111]
	v_mfma_f32_16x16x32_bf16 v[104:107], v[144:147], v[192:195], v[104:107]
	v_mfma_f32_16x16x32_bf16 v[100:103], v[160:163], v[192:195], v[100:103]
	v_mfma_f32_16x16x32_bf16 v[92:95], v[144:147], v[200:203], v[92:95]
	v_mfma_f32_16x16x32_bf16 v[84:87], v[160:163], v[200:203], v[84:87]
	v_mfma_f32_16x16x32_bf16 v[76:79], v[144:147], v[208:211], v[76:79]
	v_mfma_f32_16x16x32_bf16 v[68:71], v[160:163], v[208:211], v[68:71]
	v_mfma_f32_16x16x32_bf16 v[112:115], v[148:151], v[188:191], v[112:115]
	v_mfma_f32_16x16x32_bf16 v[108:111], v[164:167], v[188:191], v[108:111]
	v_mfma_f32_16x16x32_bf16 v[104:107], v[148:151], v[196:199], v[104:107]
	v_mfma_f32_16x16x32_bf16 v[100:103], v[164:167], v[196:199], v[100:103]
	v_mfma_f32_16x16x32_bf16 v[92:95], v[148:151], v[204:207], v[92:95]
	v_mfma_f32_16x16x32_bf16 v[84:87], v[164:167], v[204:207], v[84:87]
	v_mfma_f32_16x16x32_bf16 v[76:79], v[148:151], v[212:215], v[76:79]
	v_mfma_f32_16x16x32_bf16 v[68:71], v[164:167], v[212:215], v[68:71]
	v_mfma_f32_16x16x32_bf16 v[124:127], v[168:171], v[184:187], v[124:127]
	v_mfma_f32_16x16x32_bf16 v[120:123], v[176:179], v[184:187], v[120:123]
	v_mfma_f32_16x16x32_bf16 v[116:119], v[168:171], v[192:195], v[116:119]
	v_mfma_f32_16x16x32_bf16 v[96:99], v[176:179], v[192:195], v[96:99]
	v_mfma_f32_16x16x32_bf16 v[88:91], v[168:171], v[200:203], v[88:91]
	v_mfma_f32_16x16x32_bf16 v[80:83], v[176:179], v[200:203], v[80:83]
	v_mfma_f32_16x16x32_bf16 v[72:75], v[168:171], v[208:211], v[72:75]
	v_mfma_f32_16x16x32_bf16 v[64:67], v[176:179], v[208:211], v[64:67]
	v_mfma_f32_16x16x32_bf16 v[124:127], v[172:175], v[188:191], v[124:127]
	v_mfma_f32_16x16x32_bf16 v[120:123], v[180:183], v[188:191], v[120:123]
	v_mfma_f32_16x16x32_bf16 v[116:119], v[172:175], v[196:199], v[116:119]
	v_mfma_f32_16x16x32_bf16 v[96:99], v[180:183], v[196:199], v[96:99]
	v_mfma_f32_16x16x32_bf16 v[88:91], v[172:175], v[204:207], v[88:91]
	v_mfma_f32_16x16x32_bf16 v[80:83], v[180:183], v[204:207], v[80:83]
	v_mfma_f32_16x16x32_bf16 v[72:75], v[172:175], v[212:215], v[72:75]
	v_mfma_f32_16x16x32_bf16 v[64:67], v[180:183], v[212:215], v[64:67]
	s_barrier
	s_add_i32 s46, s55, s9
	s_mov_b32 m0, s46
	ds_read_b128 v[184:187], v157 offset:16384
	ds_read_b128 v[188:191], v157 offset:17408
	ds_read_b128 v[192:195], v157 offset:18432
	ds_read_b128 v[196:199], v157 offset:19456
	ds_read_b128 v[200:203], v157 offset:20480
	ds_read_b128 v[204:207], v157 offset:21504
	ds_read_b128 v[208:211], v157 offset:22528
	ds_read_b128 v[212:215], v157 offset:23552
	global_load_lds_dwordx4 v132, s[48:49]
	s_add_i32 m0, s46, 0x2000
	s_add_u32 s46, s48, 0x104000
	s_addc_u32 s47, s49, 0
	s_add_i32 s64, s56, s9
	global_load_lds_dwordx4 v128, s[48:49]
	s_mov_b32 m0, s64
	s_nop 0
	global_load_lds_dwordx4 v132, s[46:47]
	s_add_i32 m0, s64, 0x2000
	s_nop 0
	global_load_lds_dwordx4 v128, s[46:47]
	s_waitcnt vmcnt(4)
	s_waitcnt lgkmcnt(0)
	s_barrier
	s_waitcnt lgkmcnt(0)
	v_mfma_f32_16x16x32_bf16 v[60:63], v[144:147], v[184:187], v[60:63]
	v_mfma_f32_16x16x32_bf16 v[52:55], v[160:163], v[184:187], v[52:55]
	v_mfma_f32_16x16x32_bf16 v[44:47], v[144:147], v[192:195], v[44:47]
	v_mfma_f32_16x16x32_bf16 v[36:39], v[160:163], v[192:195], v[36:39]
	v_mfma_f32_16x16x32_bf16 v[28:31], v[144:147], v[200:203], v[28:31]
	v_mfma_f32_16x16x32_bf16 v[20:23], v[160:163], v[200:203], v[20:23]
	v_mfma_f32_16x16x32_bf16 v[12:15], v[144:147], v[208:211], v[12:15]
	v_mfma_f32_16x16x32_bf16 v[4:7], v[160:163], v[208:211], v[4:7]
	v_mfma_f32_16x16x32_bf16 v[60:63], v[148:151], v[188:191], v[60:63]
	v_mfma_f32_16x16x32_bf16 v[52:55], v[164:167], v[188:191], v[52:55]
	v_mfma_f32_16x16x32_bf16 v[44:47], v[148:151], v[196:199], v[44:47]
	v_mfma_f32_16x16x32_bf16 v[36:39], v[164:167], v[196:199], v[36:39]
	v_mfma_f32_16x16x32_bf16 v[28:31], v[148:151], v[204:207], v[28:31]
	v_mfma_f32_16x16x32_bf16 v[20:23], v[164:167], v[204:207], v[20:23]
	v_mfma_f32_16x16x32_bf16 v[12:15], v[148:151], v[212:215], v[12:15]
	v_mfma_f32_16x16x32_bf16 v[4:7], v[164:167], v[212:215], v[4:7]
	v_mfma_f32_16x16x32_bf16 v[56:59], v[168:171], v[184:187], v[56:59]
	v_mfma_f32_16x16x32_bf16 v[48:51], v[176:179], v[184:187], v[48:51]
	v_mfma_f32_16x16x32_bf16 v[40:43], v[168:171], v[192:195], v[40:43]
	v_mfma_f32_16x16x32_bf16 v[32:35], v[176:179], v[192:195], v[32:35]
	v_mfma_f32_16x16x32_bf16 v[24:27], v[168:171], v[200:203], v[24:27]
	v_mfma_f32_16x16x32_bf16 v[16:19], v[176:179], v[200:203], v[16:19]
	v_mfma_f32_16x16x32_bf16 v[8:11], v[168:171], v[208:211], v[8:11]
	v_mfma_f32_16x16x32_bf16 v[0:3], v[176:179], v[208:211], v[0:3]
	v_mfma_f32_16x16x32_bf16 v[56:59], v[172:175], v[188:191], v[56:59]
	v_mfma_f32_16x16x32_bf16 v[48:51], v[180:183], v[188:191], v[48:51]
	v_mfma_f32_16x16x32_bf16 v[40:43], v[172:175], v[196:199], v[40:43]
	v_mfma_f32_16x16x32_bf16 v[32:35], v[180:183], v[196:199], v[32:35]
	v_mfma_f32_16x16x32_bf16 v[24:27], v[172:175], v[204:207], v[24:27]
	v_mfma_f32_16x16x32_bf16 v[16:19], v[180:183], v[204:207], v[16:19]
	v_mfma_f32_16x16x32_bf16 v[8:11], v[172:175], v[212:215], v[8:11]
	v_mfma_f32_16x16x32_bf16 v[0:3], v[180:183], v[212:215], v[0:3]
	s_barrier
; #define PG8_STAGE(bufoff, gbase, voff) do { _Pragma("unroll") for (int _i = 0; _i < 2; ++_i) \
;         __builtin_amdgcn_global_load_lds((const unsigned*)((const char*)(gbase) + (voff)[_i]), (PG8_LAS unsigned*)(lds + (bufoff) + ldsw + _i * 8192), 16, 0, 0); } while (0)
; #define PG8_STAGE_NT(bufoff, gbase, voff) do { _Pragma("unroll") for (int _i = 0; _i < 2; ++_i) \
;         __builtin_amdgcn_global_load_lds((const unsigned*)((const char*)(gbase) + (voff)[_i]), (PG8_LAS unsigned*)(lds + (bufoff) + ldsw + _i * 8192), 16, 0, PG8_B_AUX); } while (0)
; #define PG8_LDA(dst, b, h) do { _Pragma("unroll") for (int m = 0; m < 4; ++m) _Pragma("unroll") for (int k = 0; k < 2; ++k) dst[m][k] = *(const PG8_LAS bf16x8*)(lds + PG8_SA(b, h) + aoff + m * 2048 + k * 1024); } while (0)
; #define PG8_LDB(dst, b, h) do { _Pragma("unroll") for (int n = 0; n < 2; ++n) _Pragma("unroll") for (int k = 0; k < 2; ++k) dst[n][k] = *(const PG8_LAS bf16x8*)(lds + PG8_SB(b, h) + boff + n * 2048 + k * 1024); } while (0)
; #define PG8_WAIT_V(n) asm volatile("s_waitcnt vmcnt(" #n ")" ::: "memory")
; #define PG8_WAIT_L(n) asm volatile("s_waitcnt lgkmcnt(" #n ")" ::: "memory")
; #define PG8_BAR __builtin_amdgcn_s_barrier()
; #define PG8_SCHED __builtin_amdgcn_sched_barrier(0)
; template <class Epi, class Sched, bool ALIGN_EPI = false, bool SP2 = false>
; __device__ __forceinline__ void gemm_phase(PG8_LAS unsigned char* lds, const Gemm g, const Sched& S, const Epi& E, int wid) {
;     ...
;         for (int t = 0; t < nt; t += 2) {
;             const bool last = (t == nt - 2);
;             const char* a1 = cA + (size_t)(t + 1) * kstep;
;             const char* a2 = last ? nA : cA + (size_t)(t + 2) * kstep; const char* b2 = last ? nB : cB + (size_t)(t + 2) * kstep;
;             const char* a3 = a2 + kstep; const char* b3 = b2 + kstep;
;             if (last && has_next) S.a_ready(nxt);
;     ...
;             PG8_LDB(B0, 1, 0); PG8_LDB(B1, 1, 1); PG8_SCHED; PG8_LDA(At, 1, 0); PG8_STAGE(PG8_SA(0, 1), a2 + hstepA, voffA);
;             PG8_WAIT_V(8); PG8_WAIT_L(0); PG8_BAR; PG8_MMA(0, 0, At, B0); PG8_MMA(0, 1, At, B1); PG8_BAR; PG8_SCHED;
;             PG8_LDA(At, 1, 1); PG8_STAGE_NT(PG8_SB(1, 0), b3, voffB); PG8_STAGE_NT(PG8_SB(1, 1), b3 + hstepB, voffB); PG8_STAGE(PG8_SA(1, 0), a3, voffA);
;             PG8_WAIT_V(8); PG8_WAIT_L(0); PG8_BAR; PG8_MMA(1, 0, At, B0); PG8_MMA(1, 1, At, B1); PG8_BAR; PG8_SCHED;
	s_add_i32 s64, 0, 0x18000
	v_add_u32_e32 v159, s64, v153
	s_add_i32 s65, 0, 0x1c000
	ds_read_b128 v[144:147], v159
	ds_read_b128 v[148:151], v159 offset:1024
	ds_read_b128 v[160:163], v159 offset:2048
	ds_read_b128 v[164:167], v159 offset:3072
	v_add_u32_e32 v159, s65, v153
	ds_read_b128 v[168:171], v159
	ds_read_b128 v[172:175], v159 offset:1024
	ds_read_b128 v[176:179], v159 offset:2048
	ds_read_b128 v[180:183], v159 offset:3072
	s_add_u32 s46, s50, 0x104000
	s_addc_u32 s47, s51, 0
	s_mov_b32 m0, s24
	ds_read_b128 v[184:187], v157 offset:32768
	ds_read_b128 v[188:191], v157 offset:33792
	ds_read_b128 v[192:195], v157 offset:34816
	ds_read_b128 v[196:199], v157 offset:35840
	ds_read_b128 v[200:203], v157 offset:36864
	ds_read_b128 v[204:207], v157 offset:37888
	ds_read_b128 v[208:211], v157 offset:38912
	ds_read_b128 v[212:215], v157 offset:39936
	global_load_lds_dwordx4 v134, s[46:47]
	s_mov_b32 m0, s25
	s_nop 0
	global_load_lds_dwordx4 v130, s[46:47]
	s_mov_b32 m0, s22
	s_nop 0
	global_load_lds_dwordx4 v134, s[50:51]
	s_mov_b32 m0, s23
	s_nop 0
	global_load_lds_dwordx4 v130, s[50:51]
	s_waitcnt vmcnt(8)
	s_waitcnt lgkmcnt(0)
	s_barrier
	s_waitcnt lgkmcnt(0)
	v_mfma_f32_16x16x32_bf16 v[112:115], v[144:147], v[184:187], v[112:115]
	v_mfma_f32_16x16x32_bf16 v[108:111], v[160:163], v[184:187], v[108:111]
	v_mfma_f32_16x16x32_bf16 v[104:107], v[144:147], v[192:195], v[104:107]
	v_mfma_f32_16x16x32_bf16 v[100:103], v[160:163], v[192:195], v[100:103]
	v_mfma_f32_16x16x32_bf16 v[92:95], v[144:147], v[200:203], v[92:95]
	v_mfma_f32_16x16x32_bf16 v[84:87], v[160:163], v[200:203], v[84:87]
	v_mfma_f32_16x16x32_bf16 v[76:79], v[144:147], v[208:211], v[76:79]
	v_mfma_f32_16x16x32_bf16 v[68:71], v[160:163], v[208:211], v[68:71]
	v_mfma_f32_16x16x32_bf16 v[112:115], v[148:151], v[188:191], v[112:115]
	v_mfma_f32_16x16x32_bf16 v[108:111], v[164:167], v[188:191], v[108:111]
	v_mfma_f32_16x16x32_bf16 v[104:107], v[148:151], v[196:199], v[104:107]
	v_mfma_f32_16x16x32_bf16 v[100:103], v[164:167], v[196:199], v[100:103]
	v_mfma_f32_16x16x32_bf16 v[92:95], v[148:151], v[204:207], v[92:95]
	v_mfma_f32_16x16x32_bf16 v[84:87], v[164:167], v[204:207], v[84:87]
	v_mfma_f32_16x16x32_bf16 v[76:79], v[148:151], v[212:215], v[76:79]
	v_mfma_f32_16x16x32_bf16 v[68:71], v[164:167], v[212:215], v[68:71]
	v_mfma_f32_16x16x32_bf16 v[124:127], v[168:171], v[184:187], v[124:127]
	v_mfma_f32_16x16x32_bf16 v[120:123], v[176:179], v[184:187], v[120:123]
	v_mfma_f32_16x16x32_bf16 v[116:119], v[168:171], v[192:195], v[116:119]
	v_mfma_f32_16x16x32_bf16 v[96:99], v[176:179], v[192:195], v[96:99]
	v_mfma_f32_16x16x32_bf16 v[88:91], v[168:171], v[200:203], v[88:91]
	v_mfma_f32_16x16x32_bf16 v[80:83], v[176:179], v[200:203], v[80:83]
	v_mfma_f32_16x16x32_bf16 v[72:75], v[168:171], v[208:211], v[72:75]
	v_mfma_f32_16x16x32_bf16 v[64:67], v[176:179], v[208:211], v[64:67]
	v_mfma_f32_16x16x32_bf16 v[124:127], v[172:175], v[188:191], v[124:127]
	v_mfma_f32_16x16x32_bf16 v[120:123], v[180:183], v[188:191], v[120:123]
	v_mfma_f32_16x16x32_bf16 v[116:119], v[172:175], v[196:199], v[116:119]
	v_mfma_f32_16x16x32_bf16 v[96:99], v[180:183], v[196:199], v[96:99]
	v_mfma_f32_16x16x32_bf16 v[88:91], v[172:175], v[204:207], v[88:91]
	v_mfma_f32_16x16x32_bf16 v[80:83], v[180:183], v[204:207], v[80:83]
	v_mfma_f32_16x16x32_bf16 v[72:75], v[172:175], v[212:215], v[72:75]
	v_mfma_f32_16x16x32_bf16 v[64:67], v[180:183], v[212:215], v[64:67]
	s_barrier
	s_add_i32 s46, s64, s9
	s_mov_b32 m0, s46
	s_add_u32 s98, s48, 0x80
	s_addc_u32 s99, s49, 0
	ds_read_b128 v[184:187], v157 offset:49152
	ds_read_b128 v[188:191], v157 offset:50176
	ds_read_b128 v[192:195], v157 offset:51200
	ds_read_b128 v[196:199], v157 offset:52224
	ds_read_b128 v[200:203], v157 offset:53248
	ds_read_b128 v[204:207], v157 offset:54272
	ds_read_b128 v[208:211], v157 offset:55296
	ds_read_b128 v[212:215], v157 offset:56320
	global_load_lds_dwordx4 v132, s[98:99]
	s_add_i32 m0, s46, 0x2000
	s_add_u32 s46, s48, 0x104080
	s_addc_u32 s47, s49, 0
	s_add_i32 s48, s65, s9
	global_load_lds_dwordx4 v128, s[98:99]
	s_mov_b32 m0, s48
	s_nop 0
	global_load_lds_dwordx4 v132, s[46:47]
	s_add_i32 m0, s48, 0x2000
	s_nop 0
	global_load_lds_dwordx4 v128, s[46:47]
	s_waitcnt vmcnt(4)
	s_waitcnt lgkmcnt(0)
	s_barrier
	s_waitcnt lgkmcnt(0)
	v_mfma_f32_16x16x32_bf16 v[60:63], v[144:147], v[184:187], v[60:63]
	v_mfma_f32_16x16x32_bf16 v[52:55], v[160:163], v[184:187], v[52:55]
	v_mfma_f32_16x16x32_bf16 v[44:47], v[144:147], v[192:195], v[44:47]
	v_mfma_f32_16x16x32_bf16 v[36:39], v[160:163], v[192:195], v[36:39]
	v_mfma_f32_16x16x32_bf16 v[28:31], v[144:147], v[200:203], v[28:31]
	v_mfma_f32_16x16x32_bf16 v[20:23], v[160:163], v[200:203], v[20:23]
	v_mfma_f32_16x16x32_bf16 v[12:15], v[144:147], v[208:211], v[12:15]
	v_mfma_f32_16x16x32_bf16 v[4:7], v[160:163], v[208:211], v[4:7]
	v_mfma_f32_16x16x32_bf16 v[60:63], v[148:151], v[188:191], v[60:63]
	v_mfma_f32_16x16x32_bf16 v[52:55], v[164:167], v[188:191], v[52:55]
	v_mfma_f32_16x16x32_bf16 v[44:47], v[148:151], v[196:199], v[44:47]
	v_mfma_f32_16x16x32_bf16 v[36:39], v[164:167], v[196:199], v[36:39]
	v_mfma_f32_16x16x32_bf16 v[28:31], v[148:151], v[204:207], v[28:31]
	v_mfma_f32_16x16x32_bf16 v[20:23], v[164:167], v[204:207], v[20:23]
	v_mfma_f32_16x16x32_bf16 v[12:15], v[148:151], v[212:215], v[12:15]
	v_mfma_f32_16x16x32_bf16 v[4:7], v[164:167], v[212:215], v[4:7]
	v_mfma_f32_16x16x32_bf16 v[56:59], v[168:171], v[184:187], v[56:59]
	v_mfma_f32_16x16x32_bf16 v[48:51], v[176:179], v[184:187], v[48:51]
	v_mfma_f32_16x16x32_bf16 v[40:43], v[168:171], v[192:195], v[40:43]
	v_mfma_f32_16x16x32_bf16 v[32:35], v[176:179], v[192:195], v[32:35]
	v_mfma_f32_16x16x32_bf16 v[24:27], v[168:171], v[200:203], v[24:27]
	v_mfma_f32_16x16x32_bf16 v[16:19], v[176:179], v[200:203], v[16:19]
	v_mfma_f32_16x16x32_bf16 v[8:11], v[168:171], v[208:211], v[8:11]
	v_mfma_f32_16x16x32_bf16 v[0:3], v[176:179], v[208:211], v[0:3]
	v_mfma_f32_16x16x32_bf16 v[56:59], v[172:175], v[188:191], v[56:59]
	v_mfma_f32_16x16x32_bf16 v[48:51], v[180:183], v[188:191], v[48:51]
	v_mfma_f32_16x16x32_bf16 v[40:43], v[172:175], v[196:199], v[40:43]
	v_mfma_f32_16x16x32_bf16 v[32:35], v[180:183], v[196:199], v[32:35]
	v_mfma_f32_16x16x32_bf16 v[24:27], v[172:175], v[204:207], v[24:27]
	v_mfma_f32_16x16x32_bf16 v[16:19], v[180:183], v[204:207], v[16:19]
	v_mfma_f32_16x16x32_bf16 v[8:11], v[172:175], v[212:215], v[8:11]
	v_mfma_f32_16x16x32_bf16 v[0:3], v[180:183], v[212:215], v[0:3]
	s_add_i32 s63, s63, 2
	s_add_u32 s61, s61, 0x100
	s_addc_u32 s62, s62, 0
	s_cmp_gt_u32 s63, 61
	s_mov_b64 s[46:47], s[4:5]
	s_cbranch_scc0 .Lrot_head_4
	s_barrier
	s_and_b64 vcc, exec, s[40:41]
	s_cbranch_vccz .LBB0_1136
	s_barrier
